# v53 + all remaining s_setprio flips deleted (F1/F2 GEMM loops and NA attention items)
# speedup vs baseline: 1.0063x; 1.0006x over previous
; #define G8_STAGE(bufoff, gbase, voff) do { _Pragma("unroll") for (int _i = 0; _i < 2; ++_i) \
;         __builtin_amdgcn_global_load_lds((const unsigned*)((const char*)(gbase) + (voff)[_i]), (LAS unsigned*)(lds + (bufoff) + ldsw + _i * 8192), 16, 0, 0); } while (0)
; #define G8_LDA(dst, b, h) do { _Pragma("unroll") for (int m = 0; m < 4; ++m) _Pragma("unroll") for (int k = 0; k < 2; ++k) dst[m][k] = *(const LAS bf16x8*)(lds + G8_SA(b, h) + aoff + m * 2048 + k * 1024); } while (0)
; #define G8_LDB(dst, b, h) do { _Pragma("unroll") for (int n = 0; n < 2; ++n) _Pragma("unroll") for (int k = 0; k < 2; ++k) dst[n][k] = *(const LAS bf16x8*)(lds + G8_SB(b, h) + boff + n * 2048 + k * 1024); } while (0)
; #define G8_MMA(ai, bj, At, Bt) do { __builtin_amdgcn_s_setprio(1); _Pragma("unroll") for (int m = 0; m < 4; ++m) _Pragma("unroll") for (int n = 0; n < 2; ++n) _Pragma("unroll") for (int k = 0; k < 2; ++k) \
;         acc[ai][bj][m][n] = __builtin_amdgcn_mfma_f32_16x16x32_bf16(Bt[n][k], At[m][k], acc[ai][bj][m][n], 0, 0, 0); __builtin_amdgcn_s_setprio(0); } while (0)
; #define G8_WAIT_V(n) asm volatile("s_waitcnt vmcnt(" #n ")" ::: "memory")
; #define G8_WAIT_L(n) asm volatile("s_waitcnt lgkmcnt(" #n ")" ::: "memory")
; template <class Epi, class Sched>
; __device__ __forceinline__ void gemm_phase(int wv, LAS unsigned char* lds, const int K, const Sched& S, const Epi& E) {
;     ...
;         for (int t = 0; t < nt; t += 2) {
;             const bool last = (t == nt - 2);
;             const char* a1 = cA + (size_t)(t + 1) * kstep;
;             const char* a2 = last ? nA : cA + (size_t)(t + 2) * kstep; const char* b2 = last ? nB : cB + (size_t)(t + 2) * kstep;
;             const char* a3 = a2 + kstep; const char* b3 = b2 + kstep;
;             G8_LDB(B0, 0, 0); G8_SCHED; G8_LDA(At, 0, 0); G8_STAGE(G8_SA(1, 1), a1 + hstep, voffA);
;             G8_WAIT_L(8); G8_BAR; G8_WAIT_L(0); G8_MMA(0, 0, At, B0); G8_BAR; G8_SCHED;
;             G8_LDB(B1, 0, 1); G8_STAGE(G8_SB(0, 0), b2, voffB);
;             G8_BAR; G8_WAIT_L(0); G8_MMA(0, 1, At, B1); G8_BAR;
;             if (full) G8_LDA(At, 0, 1); G8_STAGE(G8_SA(0, 0), a2, voffA);
;             G8_BAR; G8_WAIT_L(0); if (full) G8_MMA(1, 0, At, B0); G8_BAR; G8_SCHED;
;             G8_STAGE(G8_SB(0, 1), b2 + hstep, voffB);
;             G8_WAIT_V(6); G8_BAR; if (full) G8_MMA(1, 1, At, B1); G8_BAR;
.LBB0_606:
	s_add_u32 s22, s20, 0xfff80080
	s_addc_u32 s23, s21, -1
	s_add_i32 s49, 0, 0x10000
	v_add_u32_e32 v0, s49, v148
	ds_read_b128 v[142:145], v0
	ds_read_b128 v[150:153], v0 offset:1024
	ds_read_b128 v[154:157], v0 offset:2048
	ds_read_b128 v[158:161], v0 offset:3072
	s_cmp_eq_u32 s48, 28
	s_cselect_b32 s25, s11, s23
	s_cselect_b32 s24, s10, s22
	s_cselect_b32 s23, s15, s5
	s_cselect_b32 s22, s14, s4
	v_lshl_add_u64 v[146:147], s[20:21], 0, v[138:139]
	s_add_i32 m0, s26, 0xc000
	ds_read_b128 v[162:165], v149
	ds_read_b128 v[166:169], v149 offset:1024
	ds_read_b128 v[170:173], v149 offset:2048
	ds_read_b128 v[174:177], v149 offset:3072
	ds_read_b128 v[178:181], v149 offset:4096
	ds_read_b128 v[182:185], v149 offset:5120
	ds_read_b128 v[186:189], v149 offset:6144
	ds_read_b128 v[190:193], v149 offset:7168
	global_load_lds_dwordx4 v[146:147], off
	v_lshl_add_u64 v[146:147], s[20:21], 0, v[140:141]
	s_add_i32 m0, s26, 0xe000
	s_nop 0
	global_load_lds_dwordx4 v[146:147], off
	s_waitcnt lgkmcnt(8)
	s_barrier
	s_waitcnt lgkmcnt(0)
	s_waitcnt lgkmcnt(0)
	v_mfma_f32_16x16x32_bf16 v[126:129], v[142:145], v[162:165], v[126:129]
	v_mfma_f32_16x16x32_bf16 v[122:125], v[154:157], v[162:165], v[122:125]
	v_mfma_f32_16x16x32_bf16 v[110:113], v[142:145], v[170:173], v[110:113]
	v_mfma_f32_16x16x32_bf16 v[106:109], v[154:157], v[170:173], v[106:109]
	v_mfma_f32_16x16x32_bf16 v[94:97], v[142:145], v[178:181], v[94:97]
	v_mfma_f32_16x16x32_bf16 v[90:93], v[154:157], v[178:181], v[90:93]
	v_mfma_f32_16x16x32_bf16 v[78:81], v[142:145], v[186:189], v[78:81]
	v_mfma_f32_16x16x32_bf16 v[74:77], v[154:157], v[186:189], v[74:77]
	v_mfma_f32_16x16x32_bf16 v[126:129], v[150:153], v[166:169], v[126:129]
	v_mfma_f32_16x16x32_bf16 v[122:125], v[158:161], v[166:169], v[122:125]
	v_mfma_f32_16x16x32_bf16 v[110:113], v[150:153], v[174:177], v[110:113]
	v_mfma_f32_16x16x32_bf16 v[106:109], v[158:161], v[174:177], v[106:109]
	v_mfma_f32_16x16x32_bf16 v[94:97], v[150:153], v[182:185], v[94:97]
	v_mfma_f32_16x16x32_bf16 v[90:93], v[158:161], v[182:185], v[90:93]
	v_mfma_f32_16x16x32_bf16 v[78:81], v[150:153], v[190:193], v[78:81]
	v_mfma_f32_16x16x32_bf16 v[74:77], v[158:161], v[190:193], v[74:77]
	s_barrier
	s_add_i32 s52, 0, 0x14000
	s_add_i32 s49, s49, s3
	v_add_u32_e32 v0, s52, v148
	v_lshl_add_u64 v[146:147], s[22:23], 0, v[132:133]
	s_mov_b32 m0, s49
	ds_read_b128 v[206:209], v0
	ds_read_b128 v[210:213], v0 offset:1024
	ds_read_b128 v[214:217], v0 offset:2048
	ds_read_b128 v[218:221], v0 offset:3072
	global_load_lds_dwordx4 v[146:147], off
	v_lshl_add_u64 v[194:195], s[22:23], 0, v[136:137]
	s_add_i32 m0, s49, 0x2000
	s_nop 0
	global_load_lds_dwordx4 v[194:195], off
	s_barrier
	s_waitcnt lgkmcnt(0)
	s_waitcnt lgkmcnt(0)
	v_mfma_f32_16x16x32_bf16 v[118:121], v[206:209], v[162:165], v[118:121]
	v_mfma_f32_16x16x32_bf16 v[114:117], v[214:217], v[162:165], v[114:117]
	v_mfma_f32_16x16x32_bf16 v[102:105], v[206:209], v[170:173], v[102:105]
	v_mfma_f32_16x16x32_bf16 v[98:101], v[214:217], v[170:173], v[98:101]
	v_mfma_f32_16x16x32_bf16 v[86:89], v[206:209], v[178:181], v[86:89]
	v_mfma_f32_16x16x32_bf16 v[82:85], v[214:217], v[178:181], v[82:85]
	v_mfma_f32_16x16x32_bf16 v[70:73], v[206:209], v[186:189], v[70:73]
	v_mfma_f32_16x16x32_bf16 v[66:69], v[214:217], v[186:189], v[66:69]
	v_mfma_f32_16x16x32_bf16 v[118:121], v[210:213], v[166:169], v[118:121]
	v_mfma_f32_16x16x32_bf16 v[114:117], v[218:221], v[166:169], v[114:117]
	v_mfma_f32_16x16x32_bf16 v[102:105], v[210:213], v[174:177], v[102:105]
	v_mfma_f32_16x16x32_bf16 v[98:101], v[218:221], v[174:177], v[98:101]
	v_mfma_f32_16x16x32_bf16 v[86:89], v[210:213], v[182:185], v[86:89]
	v_mfma_f32_16x16x32_bf16 v[82:85], v[218:221], v[182:185], v[82:85]
	v_mfma_f32_16x16x32_bf16 v[70:73], v[210:213], v[190:193], v[70:73]
	v_mfma_f32_16x16x32_bf16 v[66:69], v[218:221], v[190:193], v[66:69]
	s_mov_b32 m0, s26
	v_lshl_add_u64 v[198:199], s[24:25], 0, v[130:131]
	s_barrier
	ds_read_b128 v[162:165], v149 offset:16384
	ds_read_b128 v[166:169], v149 offset:17408
	ds_read_b128 v[170:173], v149 offset:18432
	ds_read_b128 v[174:177], v149 offset:19456
	ds_read_b128 v[178:181], v149 offset:20480
	ds_read_b128 v[182:185], v149 offset:21504
	ds_read_b128 v[186:189], v149 offset:22528
	ds_read_b128 v[190:193], v149 offset:23552
	global_load_lds_dwordx4 v[198:199], off
	v_lshl_add_u64 v[200:201], s[24:25], 0, v[134:135]
	s_mov_b32 m0, s27
	s_nop 0
	global_load_lds_dwordx4 v[200:201], off
	s_barrier
	s_waitcnt lgkmcnt(0)
	s_waitcnt lgkmcnt(0)
	v_mfma_f32_16x16x32_bf16 v[62:65], v[142:145], v[162:165], v[62:65]
	v_mfma_f32_16x16x32_bf16 v[58:61], v[154:157], v[162:165], v[58:61]
	v_mfma_f32_16x16x32_bf16 v[46:49], v[142:145], v[170:173], v[46:49]
	v_mfma_f32_16x16x32_bf16 v[42:45], v[154:157], v[170:173], v[42:45]
	v_mfma_f32_16x16x32_bf16 v[30:33], v[142:145], v[178:181], v[30:33]
	v_mfma_f32_16x16x32_bf16 v[26:29], v[154:157], v[178:181], v[26:29]
	v_mfma_f32_16x16x32_bf16 v[14:17], v[142:145], v[186:189], v[14:17]
	v_mfma_f32_16x16x32_bf16 v[10:13], v[154:157], v[186:189], v[10:13]
	v_mfma_f32_16x16x32_bf16 v[62:65], v[150:153], v[166:169], v[62:65]
	v_mfma_f32_16x16x32_bf16 v[58:61], v[158:161], v[166:169], v[58:61]
	v_mfma_f32_16x16x32_bf16 v[46:49], v[150:153], v[174:177], v[46:49]
	v_mfma_f32_16x16x32_bf16 v[42:45], v[158:161], v[174:177], v[42:45]
	v_mfma_f32_16x16x32_bf16 v[30:33], v[150:153], v[182:185], v[30:33]
	v_mfma_f32_16x16x32_bf16 v[26:29], v[158:161], v[182:185], v[26:29]
	v_mfma_f32_16x16x32_bf16 v[14:17], v[150:153], v[190:193], v[14:17]
	v_mfma_f32_16x16x32_bf16 v[10:13], v[158:161], v[190:193], v[10:13]
	s_barrier
; #define G8_STAGE(bufoff, gbase, voff) do { _Pragma("unroll") for (int _i = 0; _i < 2; ++_i) \
;         __builtin_amdgcn_global_load_lds((const unsigned*)((const char*)(gbase) + (voff)[_i]), (LAS unsigned*)(lds + (bufoff) + ldsw + _i * 8192), 16, 0, 0); } while (0)
; #define G8_LDA(dst, b, h) do { _Pragma("unroll") for (int m = 0; m < 4; ++m) _Pragma("unroll") for (int k = 0; k < 2; ++k) dst[m][k] = *(const LAS bf16x8*)(lds + G8_SA(b, h) + aoff + m * 2048 + k * 1024); } while (0)
; #define G8_LDB(dst, b, h) do { _Pragma("unroll") for (int n = 0; n < 2; ++n) _Pragma("unroll") for (int k = 0; k < 2; ++k) dst[n][k] = *(const LAS bf16x8*)(lds + G8_SB(b, h) + boff + n * 2048 + k * 1024); } while (0)
; #define G8_MMA(ai, bj, At, Bt) do { __builtin_amdgcn_s_setprio(1); _Pragma("unroll") for (int m = 0; m < 4; ++m) _Pragma("unroll") for (int n = 0; n < 2; ++n) _Pragma("unroll") for (int k = 0; k < 2; ++k) \
;         acc[ai][bj][m][n] = __builtin_amdgcn_mfma_f32_16x16x32_bf16(Bt[n][k], At[m][k], acc[ai][bj][m][n], 0, 0, 0); __builtin_amdgcn_s_setprio(0); } while (0)
; #define G8_WAIT_V(n) asm volatile("s_waitcnt vmcnt(" #n ")" ::: "memory")
; #define G8_WAIT_L(n) asm volatile("s_waitcnt lgkmcnt(" #n ")" ::: "memory")
; #define G8_BAR __builtin_amdgcn_s_barrier()
; #define G8_SCHED __builtin_amdgcn_sched_barrier(0)
; template <class Epi, class Sched>
; __device__ __forceinline__ void gemm_phase(int wv, LAS unsigned char* lds, const int K, const Sched& S, const Epi& E) {
;     ...
;             G8_WAIT_V(6); G8_BAR; if (full) G8_MMA(1, 1, At, B1); G8_BAR;
;             G8_LDB(B0, 1, 0); G8_SCHED; G8_LDA(At, 1, 0); G8_STAGE(G8_SA(0, 1), a2 + hstep, voffA);
;             G8_WAIT_L(8); G8_BAR; G8_WAIT_L(0); G8_MMA(0, 0, At, B0); G8_BAR; G8_SCHED;
;             G8_LDB(B1, 1, 1); G8_STAGE(G8_SB(1, 0), b3, voffB);
;             G8_BAR; G8_WAIT_L(0); G8_MMA(0, 1, At, B1); G8_BAR;
;             if (full) G8_LDA(At, 1, 1); G8_STAGE(G8_SA(1, 0), a3, voffA);
;             G8_BAR; G8_WAIT_L(0); if (full) G8_MMA(1, 0, At, B0); G8_BAR; G8_SCHED;
	s_add_u32 s50, s22, 0x80000
	s_addc_u32 s51, s23, 0
	s_add_i32 s49, s52, s3
	v_lshl_add_u64 v[142:143], s[50:51], 0, v[132:133]
	s_mov_b32 m0, s49
	s_nop 0
	global_load_lds_dwordx4 v[142:143], off
	v_lshl_add_u64 v[142:143], s[50:51], 0, v[136:137]
	s_add_i32 m0, s49, 0x2000
	s_nop 0
	global_load_lds_dwordx4 v[142:143], off
	s_waitcnt vmcnt(6)
	s_barrier
	v_mfma_f32_16x16x32_bf16 v[54:57], v[206:209], v[162:165], v[54:57]
	v_mfma_f32_16x16x32_bf16 v[50:53], v[214:217], v[162:165], v[50:53]
	v_mfma_f32_16x16x32_bf16 v[38:41], v[206:209], v[170:173], v[38:41]
	v_mfma_f32_16x16x32_bf16 v[34:37], v[214:217], v[170:173], v[34:37]
	v_mfma_f32_16x16x32_bf16 v[22:25], v[206:209], v[178:181], v[22:25]
	v_mfma_f32_16x16x32_bf16 v[18:21], v[214:217], v[178:181], v[18:21]
	v_mfma_f32_16x16x32_bf16 v[6:9], v[206:209], v[186:189], v[6:9]
	v_mfma_f32_16x16x32_bf16 v[2:5], v[214:217], v[186:189], v[2:5]
	v_mfma_f32_16x16x32_bf16 v[54:57], v[210:213], v[166:169], v[54:57]
	v_mfma_f32_16x16x32_bf16 v[50:53], v[218:221], v[166:169], v[50:53]
	v_mfma_f32_16x16x32_bf16 v[38:41], v[210:213], v[174:177], v[38:41]
	v_mfma_f32_16x16x32_bf16 v[34:37], v[218:221], v[174:177], v[34:37]
	v_mfma_f32_16x16x32_bf16 v[22:25], v[210:213], v[182:185], v[22:25]
	v_mfma_f32_16x16x32_bf16 v[18:21], v[218:221], v[182:185], v[18:21]
	v_mfma_f32_16x16x32_bf16 v[6:9], v[210:213], v[190:193], v[6:9]
	v_mfma_f32_16x16x32_bf16 v[2:5], v[218:221], v[190:193], v[2:5]
	s_add_i32 s49, 0, 0x18000
	v_add_u32_e32 v0, s49, v148
	s_barrier
	ds_read_b128 v[142:145], v0
	ds_read_b128 v[150:153], v0 offset:1024
	ds_read_b128 v[154:157], v0 offset:2048
	ds_read_b128 v[158:161], v0 offset:3072
	s_add_u32 s24, s24, 0x80000
	s_addc_u32 s25, s25, 0
	s_mov_b32 m0, s29
	v_lshl_add_u64 v[206:207], s[24:25], 0, v[130:131]
	ds_read_b128 v[162:165], v149 offset:32768
	ds_read_b128 v[166:169], v149 offset:33792
	ds_read_b128 v[170:173], v149 offset:34816
	ds_read_b128 v[174:177], v149 offset:35840
	ds_read_b128 v[178:181], v149 offset:36864
	ds_read_b128 v[182:185], v149 offset:37888
	ds_read_b128 v[186:189], v149 offset:38912
	ds_read_b128 v[190:193], v149 offset:39936
	global_load_lds_dwordx4 v[206:207], off
	v_lshl_add_u64 v[206:207], s[24:25], 0, v[134:135]
	s_mov_b32 m0, s30
	s_nop 0
	global_load_lds_dwordx4 v[206:207], off
	s_waitcnt lgkmcnt(8)
	s_barrier
	s_waitcnt lgkmcnt(0)
	s_waitcnt lgkmcnt(0)
	v_mfma_f32_16x16x32_bf16 v[126:129], v[142:145], v[162:165], v[126:129]
	v_mfma_f32_16x16x32_bf16 v[122:125], v[154:157], v[162:165], v[122:125]
	v_mfma_f32_16x16x32_bf16 v[110:113], v[142:145], v[170:173], v[110:113]
	v_mfma_f32_16x16x32_bf16 v[106:109], v[154:157], v[170:173], v[106:109]
	v_mfma_f32_16x16x32_bf16 v[94:97], v[142:145], v[178:181], v[94:97]
	v_mfma_f32_16x16x32_bf16 v[90:93], v[154:157], v[178:181], v[90:93]
	v_mfma_f32_16x16x32_bf16 v[78:81], v[142:145], v[186:189], v[78:81]
	v_mfma_f32_16x16x32_bf16 v[74:77], v[154:157], v[186:189], v[74:77]
	v_mfma_f32_16x16x32_bf16 v[126:129], v[150:153], v[166:169], v[126:129]
	v_mfma_f32_16x16x32_bf16 v[122:125], v[158:161], v[166:169], v[122:125]
	v_mfma_f32_16x16x32_bf16 v[110:113], v[150:153], v[174:177], v[110:113]
	v_mfma_f32_16x16x32_bf16 v[106:109], v[158:161], v[174:177], v[106:109]
	v_mfma_f32_16x16x32_bf16 v[94:97], v[150:153], v[182:185], v[94:97]
	v_mfma_f32_16x16x32_bf16 v[90:93], v[158:161], v[182:185], v[90:93]
	v_mfma_f32_16x16x32_bf16 v[78:81], v[150:153], v[190:193], v[78:81]
	v_mfma_f32_16x16x32_bf16 v[74:77], v[158:161], v[190:193], v[74:77]
	s_barrier
	s_add_i32 s24, 0, 0x1c000
	s_add_i32 s25, s49, s3
	v_add_u32_e32 v0, s24, v148
	v_lshl_add_u64 v[146:147], v[146:147], 0, s[58:59]
	s_mov_b32 m0, s25
	ds_read_b128 v[206:209], v0
	ds_read_b128 v[210:213], v0 offset:1024
	ds_read_b128 v[214:217], v0 offset:2048
	ds_read_b128 v[218:221], v0 offset:3072
	global_load_lds_dwordx4 v[146:147], off
	v_lshl_add_u64 v[146:147], v[194:195], 0, s[58:59]
	s_add_i32 m0, s25, 0x2000
	s_nop 0
	global_load_lds_dwordx4 v[146:147], off
	s_barrier
	s_waitcnt lgkmcnt(0)
	s_waitcnt lgkmcnt(0)
	v_mfma_f32_16x16x32_bf16 v[118:121], v[206:209], v[162:165], v[118:121]
	v_mfma_f32_16x16x32_bf16 v[114:117], v[214:217], v[162:165], v[114:117]
	v_mfma_f32_16x16x32_bf16 v[102:105], v[206:209], v[170:173], v[102:105]
	v_mfma_f32_16x16x32_bf16 v[98:101], v[214:217], v[170:173], v[98:101]
	v_mfma_f32_16x16x32_bf16 v[86:89], v[206:209], v[178:181], v[86:89]
	v_mfma_f32_16x16x32_bf16 v[82:85], v[214:217], v[178:181], v[82:85]
	v_mfma_f32_16x16x32_bf16 v[70:73], v[206:209], v[186:189], v[70:73]
	v_mfma_f32_16x16x32_bf16 v[66:69], v[214:217], v[186:189], v[66:69]
	v_mfma_f32_16x16x32_bf16 v[118:121], v[210:213], v[166:169], v[118:121]
	v_mfma_f32_16x16x32_bf16 v[114:117], v[218:221], v[166:169], v[114:117]
	v_mfma_f32_16x16x32_bf16 v[102:105], v[210:213], v[174:177], v[102:105]
	v_mfma_f32_16x16x32_bf16 v[98:101], v[218:221], v[174:177], v[98:101]
	v_mfma_f32_16x16x32_bf16 v[86:89], v[210:213], v[182:185], v[86:89]
	v_mfma_f32_16x16x32_bf16 v[82:85], v[218:221], v[182:185], v[82:85]
	v_mfma_f32_16x16x32_bf16 v[70:73], v[210:213], v[190:193], v[70:73]
	v_mfma_f32_16x16x32_bf16 v[66:69], v[218:221], v[190:193], v[66:69]
	s_mov_b32 m0, s35
	v_lshl_add_u64 v[146:147], v[198:199], 0, s[58:59]
	s_barrier
; __device__ __forceinline__ unsigned pk_bf16(float lo, float hi) { unsigned r; asm volatile("v_cvt_pk_bf16_f32 %0, %1, %2" : "=v"(r) : "v"(lo), "v"(hi)); return r; }
; __device__ __forceinline__ int otid(int wv) { int ln; asm volatile("v_mbcnt_lo_u32_b32 %0, -1, 0\n\tv_mbcnt_hi_u32_b32 %0, -1, %0" : "=v"(ln)); return wv * 64 + ln; }
; #define G8_STAGE(bufoff, gbase, voff) do { _Pragma("unroll") for (int _i = 0; _i < 2; ++_i) \
;         __builtin_amdgcn_global_load_lds((const unsigned*)((const char*)(gbase) + (voff)[_i]), (LAS unsigned*)(lds + (bufoff) + ldsw + _i * 8192), 16, 0, 0); } while (0)
; template <class Epi, class Sched>
; __device__ __forceinline__ void gemm_phase(int wv, LAS unsigned char* lds, const int K, const Sched& S, const Epi& E) {
;     ...
;             G8_BAR; G8_WAIT_L(0); if (full) G8_MMA(1, 0, At, B0); G8_BAR; G8_SCHED;
;             G8_STAGE(G8_SB(1, 1), b3 + hstep, voffB);
;             G8_WAIT_V(6); G8_BAR; if (full) G8_MMA(1, 1, At, B1); G8_BAR;
;         }
;         { const int t2 = otid(wv); E(acc, cur, wr, wc, t2 & 15, (t2 >> 4) & 3); }
;         if (!has_next) break;
;     __device__ __forceinline__ void operator()(const f32x4 (&acc)[2][2][4][2], const Unit& u, int wr, int wc, int fr, int fq) const {
;         const int row0 = wr * 64 + fr, col0 = wc * 32 + 8 * fq;
; #pragma unroll
;         for (int ai = 0; ai < 2; ++ai) if (ai == 0 || u.half == 0)
; #pragma unroll
;             for (int m = 0; m < 4; ++m) { const int rr = row0 + ai * HALF + m * 16; bf16_t* rowp = (bf16_t*)u.o + (size_t)rr * u.ldo + col0;
;                 const int k = u.mk + rr; const bool mir = (u.mk >= 0) && (k > 0);
;                 bf16_t* rowm = (bf16_t*)u.p1 + (size_t)(2048 - k) * u.ldo + col0;
; #pragma unroll
;                 for (int bj = 0; bj < 2; ++bj) { if (col0 + bj * HALF < u.cmax) { const f32x4 v0 = acc[ai][bj][m][0], v1 = acc[ai][bj][m][1];
;                     u32x4 w; w.x = pk_bf16(v0[0], v0[1]); w.y = pk_bf16(v0[2], v0[3]); w.z = pk_bf16(v1[0], v1[1]); w.w = pk_bf16(v1[2], v1[3]);
;                     st16_wt(rowp + bj * HALF, w);
;                     if (mir) { const float sg = u.mneg ? -1.f : 1.f; u32x4 w2; w2.x = pk_bf16(v0[0] * sg, v0[1] * sg); w2.y = pk_bf16(v0[2] * sg, v0[3] * sg); w2.z = pk_bf16(v1[0] * sg, v1[1] * sg); w2.w = pk_bf16(v1[2] * sg, v1[3] * sg);
;                         st16_wt(rowm + bj * HALF, w2); } } } }
	ds_read_b128 v[162:165], v149 offset:49152
	ds_read_b128 v[166:169], v149 offset:50176
	ds_read_b128 v[170:173], v149 offset:51200
	ds_read_b128 v[174:177], v149 offset:52224
	ds_read_b128 v[178:181], v149 offset:53248
	ds_read_b128 v[182:185], v149 offset:54272
	ds_read_b128 v[186:189], v149 offset:55296
	ds_read_b128 v[190:193], v149 offset:56320
	global_load_lds_dwordx4 v[146:147], off
	v_lshl_add_u64 v[146:147], v[200:201], 0, s[58:59]
	s_mov_b32 m0, s36
	s_nop 0
	global_load_lds_dwordx4 v[146:147], off
	s_barrier
	s_waitcnt lgkmcnt(0)
	s_waitcnt lgkmcnt(0)
	v_mfma_f32_16x16x32_bf16 v[62:65], v[142:145], v[162:165], v[62:65]
	v_mfma_f32_16x16x32_bf16 v[58:61], v[154:157], v[162:165], v[58:61]
	v_mfma_f32_16x16x32_bf16 v[46:49], v[142:145], v[170:173], v[46:49]
	v_mfma_f32_16x16x32_bf16 v[42:45], v[154:157], v[170:173], v[42:45]
	v_mfma_f32_16x16x32_bf16 v[30:33], v[142:145], v[178:181], v[30:33]
	v_mfma_f32_16x16x32_bf16 v[26:29], v[154:157], v[178:181], v[26:29]
	v_mfma_f32_16x16x32_bf16 v[14:17], v[142:145], v[186:189], v[14:17]
	v_mfma_f32_16x16x32_bf16 v[10:13], v[154:157], v[186:189], v[10:13]
	v_mfma_f32_16x16x32_bf16 v[62:65], v[150:153], v[166:169], v[62:65]
	v_mfma_f32_16x16x32_bf16 v[58:61], v[158:161], v[166:169], v[58:61]
	v_mfma_f32_16x16x32_bf16 v[46:49], v[150:153], v[174:177], v[46:49]
	v_mfma_f32_16x16x32_bf16 v[42:45], v[158:161], v[174:177], v[42:45]
	v_mfma_f32_16x16x32_bf16 v[30:33], v[150:153], v[182:185], v[30:33]
	v_mfma_f32_16x16x32_bf16 v[26:29], v[158:161], v[182:185], v[26:29]
	v_mfma_f32_16x16x32_bf16 v[14:17], v[150:153], v[190:193], v[14:17]
	v_mfma_f32_16x16x32_bf16 v[10:13], v[158:161], v[190:193], v[10:13]
	s_barrier
	s_add_u32 s22, s22, 0x80080
	s_addc_u32 s23, s23, 0
	s_add_i32 s24, s24, s3
	v_lshl_add_u64 v[142:143], s[22:23], 0, v[132:133]
	s_mov_b32 m0, s24
	s_nop 0
	global_load_lds_dwordx4 v[142:143], off
	v_lshl_add_u64 v[142:143], s[22:23], 0, v[136:137]
	s_add_i32 m0, s24, 0x2000
	s_nop 0
	global_load_lds_dwordx4 v[142:143], off
	s_waitcnt vmcnt(6)
	s_barrier
	v_mfma_f32_16x16x32_bf16 v[54:57], v[206:209], v[162:165], v[54:57]
	v_mfma_f32_16x16x32_bf16 v[50:53], v[214:217], v[162:165], v[50:53]
	v_mfma_f32_16x16x32_bf16 v[38:41], v[206:209], v[170:173], v[38:41]
	v_mfma_f32_16x16x32_bf16 v[34:37], v[214:217], v[170:173], v[34:37]
	v_mfma_f32_16x16x32_bf16 v[22:25], v[206:209], v[178:181], v[22:25]
	v_mfma_f32_16x16x32_bf16 v[18:21], v[214:217], v[178:181], v[18:21]
	v_mfma_f32_16x16x32_bf16 v[6:9], v[206:209], v[186:189], v[6:9]
	v_mfma_f32_16x16x32_bf16 v[2:5], v[214:217], v[186:189], v[2:5]
	v_mfma_f32_16x16x32_bf16 v[54:57], v[210:213], v[166:169], v[54:57]
	v_mfma_f32_16x16x32_bf16 v[50:53], v[218:221], v[166:169], v[50:53]
	v_mfma_f32_16x16x32_bf16 v[38:41], v[210:213], v[174:177], v[38:41]
	v_mfma_f32_16x16x32_bf16 v[34:37], v[218:221], v[174:177], v[34:37]
	v_mfma_f32_16x16x32_bf16 v[22:25], v[210:213], v[182:185], v[22:25]
	v_mfma_f32_16x16x32_bf16 v[18:21], v[218:221], v[182:185], v[18:21]
	v_mfma_f32_16x16x32_bf16 v[6:9], v[210:213], v[190:193], v[6:9]
	v_mfma_f32_16x16x32_bf16 v[2:5], v[218:221], v[190:193], v[2:5]
	s_add_i32 s48, s48, 2
	s_add_u32 s20, s20, 0x100
	s_addc_u32 s21, s21, 0
	s_add_u32 s4, s4, 0x100
	s_addc_u32 s5, s5, 0
	s_cmp_gt_u32 s48, 29
	s_barrier
	s_cbranch_scc0 .LBB0_606
	v_mbcnt_lo_u32_b32 v0, -1, 0
	v_mbcnt_hi_u32_b32 v0, -1, v0
	v_cvt_pk_bf16_f32 v150, v126, v127
	v_cvt_pk_bf16_f32 v151, v128, v129
	v_cvt_pk_bf16_f32 v152, v122, v123
	v_cvt_pk_bf16_f32 v153, v124, v125
	s_nop 0
	v_and_or_b32 v142, v0, 15, s31
	v_lshrrev_b32_e32 v0, 1, v0
	v_ashrrev_i32_e32 v143, 31, v142
	v_and_or_b32 v0, v0, 24, s34
	v_lshlrev_b64 v[144:145], 10, v[142:143]
	v_lshl_add_u64 v[144:145], s[8:9], 0, v[144:145]
	v_lshlrev_b32_e32 v0, 1, v0
	v_add_u32_e32 v143, s28, v142
	v_lshl_add_u64 v[146:147], v[144:145], 0, v[0:1]
	v_sub_u32_e32 v144, 0x800, v143
	v_ashrrev_i32_e32 v145, 31, v144
	v_lshlrev_b64 v[144:145], 10, v[144:145]
	v_lshl_add_u64 v[144:145], s[6:7], 0, v[144:145]
	v_cmp_lt_i32_e32 vcc, 0, v143
	v_lshl_add_u64 v[144:145], v[144:145], 0, v[0:1]
	global_store_dwordx4 v[146:147], v[150:153], off
	s_and_saveexec_b64 s[4:5], vcc
	s_cbranch_execz .LBB0_609
	s_cmp_eq_u32 s1, 0
	s_cselect_b64 s[20:21], -1, 0
	v_cndmask_b32_e64 v143, -1.0, 1.0, s[20:21]
	v_mul_f32_e32 v126, v143, v126
	v_mul_f32_e32 v127, v143, v127
	v_cvt_pk_bf16_f32 v126, v126, v127
	v_mul_f32_e32 v127, v143, v128
	v_mul_f32_e32 v128, v143, v129
	v_mul_f32_e32 v122, v143, v122
	v_mul_f32_e32 v123, v143, v123
	v_cvt_pk_bf16_f32 v127, v127, v128
	v_cvt_pk_bf16_f32 v128, v122, v123
	v_mul_f32_e32 v122, v143, v124
	v_mul_f32_e32 v123, v143, v125
	v_cvt_pk_bf16_f32 v129, v122, v123
	global_store_dwordx4 v[144:145], v[126:129], off

; #define G8_STAGE(bufoff, gbase, voff) do { _Pragma("unroll") for (int _i = 0; _i < 2; ++_i) \
;         __builtin_amdgcn_global_load_lds((const unsigned*)((const char*)(gbase) + (voff)[_i]), (LAS unsigned*)(lds + (bufoff) + ldsw + _i * 8192), 16, 0, 0); } while (0)
; #define G8_LDA(dst, b, h) do { _Pragma("unroll") for (int m = 0; m < 4; ++m) _Pragma("unroll") for (int k = 0; k < 2; ++k) dst[m][k] = *(const LAS bf16x8*)(lds + G8_SA(b, h) + aoff + m * 2048 + k * 1024); } while (0)
; #define G8_LDB(dst, b, h) do { _Pragma("unroll") for (int n = 0; n < 2; ++n) _Pragma("unroll") for (int k = 0; k < 2; ++k) dst[n][k] = *(const LAS bf16x8*)(lds + G8_SB(b, h) + boff + n * 2048 + k * 1024); } while (0)
; #define G8_WAIT_V(n) asm volatile("s_waitcnt vmcnt(" #n ")" ::: "memory")
; #define G8_WAIT_L(n) asm volatile("s_waitcnt lgkmcnt(" #n ")" ::: "memory")
; #define G8_BAR __builtin_amdgcn_s_barrier()
; #define G8_SCHED __builtin_amdgcn_sched_barrier(0)
; template <class Epi, class Sched>
; __device__ __forceinline__ void gemm_phase(int wv, LAS unsigned char* lds, const int K, const Sched& S, const Epi& E) {
;     ...
;             G8_LDB(B0, 0, 0); G8_SCHED; G8_LDA(At, 0, 0); G8_STAGE(G8_SA(1, 1), a1 + hstep, voffA);
;             G8_WAIT_L(8); G8_BAR; G8_WAIT_L(0); G8_MMA(0, 0, At, B0); G8_BAR; G8_SCHED;
;             G8_LDB(B1, 0, 1); G8_STAGE(G8_SB(0, 0), b2, voffB);
;             G8_BAR; G8_WAIT_L(0); G8_MMA(0, 1, At, B1); G8_BAR;
;             if (full) G8_LDA(At, 0, 1); G8_STAGE(G8_SA(0, 0), a2, voffA);
;             G8_BAR; G8_WAIT_L(0); if (full) G8_MMA(1, 0, At, B0); G8_BAR; G8_SCHED;
;             G8_STAGE(G8_SB(0, 1), b2 + hstep, voffB);
;             G8_WAIT_V(6); G8_BAR; if (full) G8_MMA(1, 1, At, B1); G8_BAR;
;             G8_LDB(B0, 1, 0); G8_SCHED; G8_LDA(At, 1, 0); G8_STAGE(G8_SA(0, 1), a2 + hstep, voffA);
;             G8_WAIT_L(8); G8_BAR; G8_WAIT_L(0); G8_MMA(0, 0, At, B0); G8_BAR; G8_SCHED;
;             G8_LDB(B1, 1, 1); G8_STAGE(G8_SB(1, 0), b3, voffB);
;             G8_BAR; G8_WAIT_L(0); G8_MMA(0, 1, At, B1); G8_BAR;
;             if (full) G8_LDA(At, 1, 1); G8_STAGE(G8_SA(1, 0), a3, voffA);
;             G8_BAR; G8_WAIT_L(0); if (full) G8_MMA(1, 0, At, B0); G8_BAR; G8_SCHED;
;             G8_STAGE(G8_SB(1, 1), b3 + hstep, voffB);
;             G8_WAIT_V(6); G8_BAR; if (full) G8_MMA(1, 1, At, B1); G8_BAR;
.LBB0_648:
	s_add_i32 s39, 0, 0x10000
	v_add_u32_e32 v0, s39, v64
	ds_read_b128 v[2:5], v0
	ds_read_b128 v[6:9], v0 offset:1024
	ds_read_b128 v[10:13], v0 offset:2048
	ds_read_b128 v[14:17], v0 offset:3072
	s_add_u32 s4, s18, 0x10080
	s_addc_u32 s5, s19, 0
	s_add_i32 s40, s25, 0xc000
	v_lshl_add_u64 v[50:51], s[4:5], 0, v[60:61]
	s_mov_b32 m0, s40
	ds_read_b128 v[18:21], v65
	ds_read_b128 v[22:25], v65 offset:1024
	ds_read_b128 v[26:29], v65 offset:2048
	ds_read_b128 v[30:33], v65 offset:3072
	ds_read_b128 v[34:37], v65 offset:4096
	ds_read_b128 v[38:41], v65 offset:5120
	ds_read_b128 v[42:45], v65 offset:6144
	ds_read_b128 v[46:49], v65 offset:7168
	global_load_lds_dwordx4 v[50:51], off
	v_lshl_add_u64 v[50:51], s[4:5], 0, v[56:57]
	s_add_i32 s4, s25, 0xe000
	s_mov_b32 m0, s4
	s_nop 0
	global_load_lds_dwordx4 v[50:51], off
	s_waitcnt lgkmcnt(8)
	s_barrier
	s_waitcnt lgkmcnt(0)
	s_waitcnt lgkmcnt(0)
	v_mfma_f32_16x16x32_bf16 v[50:53], v[2:5], v[18:21], 0
	v_mfma_f32_16x16x32_bf16 v[66:69], v[10:13], v[18:21], 0
	v_mfma_f32_16x16x32_bf16 v[70:73], v[2:5], v[26:29], 0
	v_mfma_f32_16x16x32_bf16 v[74:77], v[10:13], v[26:29], 0
	v_mfma_f32_16x16x32_bf16 v[78:81], v[2:5], v[34:37], 0
	v_mfma_f32_16x16x32_bf16 v[82:85], v[10:13], v[34:37], 0
	v_mfma_f32_16x16x32_bf16 v[86:89], v[2:5], v[42:45], 0
	v_mfma_f32_16x16x32_bf16 v[90:93], v[10:13], v[42:45], 0
	v_mfma_f32_16x16x32_bf16 v[50:53], v[6:9], v[22:25], v[50:53]
	v_mfma_f32_16x16x32_bf16 v[66:69], v[14:17], v[22:25], v[66:69]
	v_mfma_f32_16x16x32_bf16 v[70:73], v[6:9], v[30:33], v[70:73]
	v_mfma_f32_16x16x32_bf16 v[74:77], v[14:17], v[30:33], v[74:77]
	v_mfma_f32_16x16x32_bf16 v[78:81], v[6:9], v[38:41], v[78:81]
	v_mfma_f32_16x16x32_bf16 v[82:85], v[14:17], v[38:41], v[82:85]
	v_mfma_f32_16x16x32_bf16 v[86:89], v[6:9], v[46:49], v[86:89]
	v_mfma_f32_16x16x32_bf16 v[90:93], v[14:17], v[46:49], v[90:93]
	s_barrier
	s_add_i32 s41, 0, 0x14000
	v_lshl_add_u64 v[62:63], s[20:21], 0, v[58:59]
	s_add_i32 s39, s39, s1
	v_add_u32_e32 v204, s41, v64
	v_lshl_add_u64 v[110:111], v[62:63], 0, s[60:61]
	s_mov_b32 m0, s39
	v_lshl_add_u64 v[194:195], s[20:21], 0, v[54:55]
	s_add_i32 s5, s39, 0x2000
	ds_read_b128 v[94:97], v204
	ds_read_b128 v[98:101], v204 offset:1024
	ds_read_b128 v[102:105], v204 offset:2048
	ds_read_b128 v[106:109], v204 offset:3072
	global_load_lds_dwordx4 v[110:111], off
	v_lshl_add_u64 v[110:111], v[194:195], 0, s[60:61]
	s_mov_b32 m0, s5
	s_nop 0
	global_load_lds_dwordx4 v[110:111], off
	s_barrier
	s_waitcnt lgkmcnt(0)
	s_waitcnt lgkmcnt(0)
	v_mfma_f32_16x16x32_bf16 v[110:113], v[94:97], v[18:21], 0
	v_mfma_f32_16x16x32_bf16 v[18:21], v[102:105], v[18:21], 0
	v_mfma_f32_16x16x32_bf16 v[110:113], v[98:101], v[22:25], v[110:113]
	v_mfma_f32_16x16x32_bf16 v[18:21], v[106:109], v[22:25], v[18:21]
	v_mfma_f32_16x16x32_bf16 v[22:25], v[94:97], v[26:29], 0
	v_mfma_f32_16x16x32_bf16 v[26:29], v[102:105], v[26:29], 0
	v_mfma_f32_16x16x32_bf16 v[22:25], v[98:101], v[30:33], v[22:25]
	v_mfma_f32_16x16x32_bf16 v[26:29], v[106:109], v[30:33], v[26:29]
	v_mfma_f32_16x16x32_bf16 v[30:33], v[94:97], v[34:37], 0
	v_mfma_f32_16x16x32_bf16 v[34:37], v[102:105], v[34:37], 0
	v_mfma_f32_16x16x32_bf16 v[30:33], v[98:101], v[38:41], v[30:33]
	v_mfma_f32_16x16x32_bf16 v[34:37], v[106:109], v[38:41], v[34:37]
	v_mfma_f32_16x16x32_bf16 v[38:41], v[94:97], v[42:45], 0
	v_mfma_f32_16x16x32_bf16 v[42:45], v[102:105], v[42:45], 0
	v_mfma_f32_16x16x32_bf16 v[38:41], v[98:101], v[46:49], v[38:41]
	v_mfma_f32_16x16x32_bf16 v[42:45], v[106:109], v[46:49], v[42:45]
	v_lshl_add_u64 v[198:199], s[18:19], 0, v[60:61]
	s_mov_b32 m0, s25
	v_lshl_add_u64 v[142:143], v[198:199], 0, s[60:61]
	v_lshl_add_u64 v[200:201], s[18:19], 0, v[56:57]
	s_barrier
	ds_read_b128 v[46:49], v65 offset:16384
	ds_read_b128 v[114:117], v65 offset:17408
	ds_read_b128 v[118:121], v65 offset:18432
	ds_read_b128 v[122:125], v65 offset:19456
	ds_read_b128 v[126:129], v65 offset:20480
	ds_read_b128 v[130:133], v65 offset:21504
	ds_read_b128 v[134:137], v65 offset:22528
	ds_read_b128 v[138:141], v65 offset:23552
	global_load_lds_dwordx4 v[142:143], off
	v_lshl_add_u64 v[142:143], v[200:201], 0, s[60:61]
	s_mov_b32 m0, s26
	s_nop 0
	global_load_lds_dwordx4 v[142:143], off
	s_barrier
	s_waitcnt lgkmcnt(0)
	s_waitcnt lgkmcnt(0)
	v_mfma_f32_16x16x32_bf16 v[142:145], v[2:5], v[46:49], 0
	v_mfma_f32_16x16x32_bf16 v[150:153], v[2:5], v[118:121], 0
	v_mfma_f32_16x16x32_bf16 v[158:161], v[2:5], v[126:129], 0
	v_mfma_f32_16x16x32_bf16 v[2:5], v[2:5], v[134:137], 0
	v_mfma_f32_16x16x32_bf16 v[142:145], v[6:9], v[114:117], v[142:145]
	v_mfma_f32_16x16x32_bf16 v[146:149], v[10:13], v[46:49], 0
	v_mfma_f32_16x16x32_bf16 v[150:153], v[6:9], v[122:125], v[150:153]
	v_mfma_f32_16x16x32_bf16 v[154:157], v[10:13], v[118:121], 0
	v_mfma_f32_16x16x32_bf16 v[158:161], v[6:9], v[130:133], v[158:161]
	v_mfma_f32_16x16x32_bf16 v[162:165], v[10:13], v[126:129], 0
	v_mfma_f32_16x16x32_bf16 v[2:5], v[6:9], v[138:141], v[2:5]
	v_mfma_f32_16x16x32_bf16 v[6:9], v[10:13], v[134:137], 0
	v_mfma_f32_16x16x32_bf16 v[146:149], v[14:17], v[114:117], v[146:149]
	v_mfma_f32_16x16x32_bf16 v[154:157], v[14:17], v[122:125], v[154:157]
	v_mfma_f32_16x16x32_bf16 v[162:165], v[14:17], v[130:133], v[162:165]
	v_mfma_f32_16x16x32_bf16 v[6:9], v[14:17], v[138:141], v[6:9]
	s_barrier
	s_add_u32 s42, s20, 0x10100
	s_addc_u32 s43, s21, 0
	s_add_i32 s41, s41, s1
	v_lshl_add_u64 v[10:11], s[42:43], 0, v[58:59]
	s_mov_b32 m0, s41
	s_add_i32 s38, s41, 0x2000
	global_load_lds_dwordx4 v[10:11], off
	v_lshl_add_u64 v[10:11], s[42:43], 0, v[54:55]
	s_mov_b32 m0, s38
	s_nop 0
	global_load_lds_dwordx4 v[10:11], off
	s_waitcnt vmcnt(6)
	s_barrier
; #define G8_STAGE(bufoff, gbase, voff) do { _Pragma("unroll") for (int _i = 0; _i < 2; ++_i) \
;         __builtin_amdgcn_global_load_lds((const unsigned*)((const char*)(gbase) + (voff)[_i]), (LAS unsigned*)(lds + (bufoff) + ldsw + _i * 8192), 16, 0, 0); } while (0)
; #define G8_LDA(dst, b, h) do { _Pragma("unroll") for (int m = 0; m < 4; ++m) _Pragma("unroll") for (int k = 0; k < 2; ++k) dst[m][k] = *(const LAS bf16x8*)(lds + G8_SA(b, h) + aoff + m * 2048 + k * 1024); } while (0)
; #define G8_LDB(dst, b, h) do { _Pragma("unroll") for (int n = 0; n < 2; ++n) _Pragma("unroll") for (int k = 0; k < 2; ++k) dst[n][k] = *(const LAS bf16x8*)(lds + G8_SB(b, h) + boff + n * 2048 + k * 1024); } while (0)
; #define G8_MMA(ai, bj, At, Bt) do { __builtin_amdgcn_s_setprio(1); _Pragma("unroll") for (int m = 0; m < 4; ++m) _Pragma("unroll") for (int n = 0; n < 2; ++n) _Pragma("unroll") for (int k = 0; k < 2; ++k) \
;         acc[ai][bj][m][n] = __builtin_amdgcn_mfma_f32_16x16x32_bf16(Bt[n][k], At[m][k], acc[ai][bj][m][n], 0, 0, 0); __builtin_amdgcn_s_setprio(0); } while (0)
; #define G8_WAIT_V(n) asm volatile("s_waitcnt vmcnt(" #n ")" ::: "memory")
; #define G8_WAIT_L(n) asm volatile("s_waitcnt lgkmcnt(" #n ")" ::: "memory")
; #define G8_BAR __builtin_amdgcn_s_barrier()
; #define G8_SCHED __builtin_amdgcn_sched_barrier(0)
; template <class Epi, class Sched>
; __device__ __forceinline__ void gemm_phase(int wv, LAS unsigned char* lds, const int K, const Sched& S, const Epi& E) {
;     ...
;             G8_WAIT_V(6); G8_BAR; if (full) G8_MMA(1, 1, At, B1); G8_BAR;
;             G8_LDB(B0, 1, 0); G8_SCHED; G8_LDA(At, 1, 0); G8_STAGE(G8_SA(0, 1), a2 + hstep, voffA);
;             G8_WAIT_L(8); G8_BAR; G8_WAIT_L(0); G8_MMA(0, 0, At, B0); G8_BAR; G8_SCHED;
;             G8_LDB(B1, 1, 1); G8_STAGE(G8_SB(1, 0), b3, voffB);
;             G8_BAR; G8_WAIT_L(0); G8_MMA(0, 1, At, B1); G8_BAR;
;             if (full) G8_LDA(At, 1, 1); G8_STAGE(G8_SA(1, 0), a3, voffA);
;             G8_BAR; G8_WAIT_L(0); if (full) G8_MMA(1, 0, At, B0); G8_BAR; G8_SCHED;
	v_mfma_f32_16x16x32_bf16 v[10:13], v[94:97], v[46:49], 0
	v_mfma_f32_16x16x32_bf16 v[14:17], v[102:105], v[46:49], 0
	v_mfma_f32_16x16x32_bf16 v[10:13], v[98:101], v[114:117], v[10:13]
	v_mfma_f32_16x16x32_bf16 v[14:17], v[106:109], v[114:117], v[14:17]
	v_mfma_f32_16x16x32_bf16 v[46:49], v[94:97], v[118:121], 0
	v_mfma_f32_16x16x32_bf16 v[114:117], v[102:105], v[118:121], 0
	v_mfma_f32_16x16x32_bf16 v[118:121], v[94:97], v[126:129], 0
	v_mfma_f32_16x16x32_bf16 v[94:97], v[94:97], v[134:137], 0
	v_mfma_f32_16x16x32_bf16 v[46:49], v[98:101], v[122:125], v[46:49]
	v_mfma_f32_16x16x32_bf16 v[114:117], v[106:109], v[122:125], v[114:117]
	v_mfma_f32_16x16x32_bf16 v[118:121], v[98:101], v[130:133], v[118:121]
	v_mfma_f32_16x16x32_bf16 v[122:125], v[102:105], v[126:129], 0
	v_mfma_f32_16x16x32_bf16 v[94:97], v[98:101], v[138:141], v[94:97]
	v_mfma_f32_16x16x32_bf16 v[98:101], v[102:105], v[134:137], 0
	v_mfma_f32_16x16x32_bf16 v[122:125], v[106:109], v[130:133], v[122:125]
	v_mfma_f32_16x16x32_bf16 v[98:101], v[106:109], v[138:141], v[98:101]
	s_add_i32 s46, 0, 0x18000
	v_add_u32_e32 v218, s46, v64
	s_barrier
	ds_read_b128 v[102:105], v218
	ds_read_b128 v[106:109], v218 offset:1024
	ds_read_b128 v[126:129], v218 offset:2048
	ds_read_b128 v[130:133], v218 offset:3072
	s_add_u32 s42, s18, 0x10100
	s_addc_u32 s43, s19, 0
	s_mov_b32 m0, s27
	v_lshl_add_u64 v[190:191], s[42:43], 0, v[60:61]
	ds_read_b128 v[134:137], v65 offset:32768
	ds_read_b128 v[138:141], v65 offset:33792
	ds_read_b128 v[166:169], v65 offset:34816
	ds_read_b128 v[170:173], v65 offset:35840
	ds_read_b128 v[174:177], v65 offset:36864
	ds_read_b128 v[178:181], v65 offset:37888
	ds_read_b128 v[182:185], v65 offset:38912
	ds_read_b128 v[186:189], v65 offset:39936
	global_load_lds_dwordx4 v[190:191], off
	v_lshl_add_u64 v[190:191], s[42:43], 0, v[56:57]
	s_mov_b32 m0, s28
	s_nop 0
	global_load_lds_dwordx4 v[190:191], off
	s_waitcnt lgkmcnt(8)
	s_barrier
	s_waitcnt lgkmcnt(0)
	s_waitcnt lgkmcnt(0)
	v_mfma_f32_16x16x32_bf16 v[50:53], v[102:105], v[134:137], v[50:53]
	v_mfma_f32_16x16x32_bf16 v[66:69], v[126:129], v[134:137], v[66:69]
	v_mfma_f32_16x16x32_bf16 v[70:73], v[102:105], v[166:169], v[70:73]
	v_mfma_f32_16x16x32_bf16 v[74:77], v[126:129], v[166:169], v[74:77]
	v_mfma_f32_16x16x32_bf16 v[78:81], v[102:105], v[174:177], v[78:81]
	v_mfma_f32_16x16x32_bf16 v[82:85], v[126:129], v[174:177], v[82:85]
	v_mfma_f32_16x16x32_bf16 v[86:89], v[102:105], v[182:185], v[86:89]
	v_mfma_f32_16x16x32_bf16 v[90:93], v[126:129], v[182:185], v[90:93]
	v_mfma_f32_16x16x32_bf16 v[50:53], v[106:109], v[138:141], v[50:53]
	v_mfma_f32_16x16x32_bf16 v[66:69], v[130:133], v[138:141], v[66:69]
	v_mfma_f32_16x16x32_bf16 v[70:73], v[106:109], v[170:173], v[70:73]
	v_mfma_f32_16x16x32_bf16 v[74:77], v[130:133], v[170:173], v[74:77]
	v_mfma_f32_16x16x32_bf16 v[78:81], v[106:109], v[178:181], v[78:81]
	v_mfma_f32_16x16x32_bf16 v[82:85], v[130:133], v[178:181], v[82:85]
	v_mfma_f32_16x16x32_bf16 v[86:89], v[106:109], v[186:189], v[86:89]
	v_mfma_f32_16x16x32_bf16 v[90:93], v[130:133], v[186:189], v[90:93]
	s_barrier
	s_add_i32 s48, 0, 0x1c000
	s_add_i32 s43, s46, s1
	v_add_u32_e32 v219, s48, v64
	v_lshl_add_u64 v[62:63], v[62:63], 0, s[64:65]
	s_mov_b32 m0, s43
	s_add_i32 s42, s43, 0x2000
	ds_read_b128 v[190:193], v219
	ds_read_b128 v[206:209], v219 offset:1024
	ds_read_b128 v[210:213], v219 offset:2048
	ds_read_b128 v[214:217], v219 offset:3072
	global_load_lds_dwordx4 v[62:63], off
	v_lshl_add_u64 v[62:63], v[194:195], 0, s[64:65]
	s_mov_b32 m0, s42
	s_nop 0
	global_load_lds_dwordx4 v[62:63], off
	s_barrier
	s_waitcnt lgkmcnt(0)
	s_waitcnt lgkmcnt(0)
	v_mfma_f32_16x16x32_bf16 v[110:113], v[190:193], v[134:137], v[110:113]
	v_mfma_f32_16x16x32_bf16 v[18:21], v[210:213], v[134:137], v[18:21]
	v_mfma_f32_16x16x32_bf16 v[22:25], v[190:193], v[166:169], v[22:25]
	v_mfma_f32_16x16x32_bf16 v[26:29], v[210:213], v[166:169], v[26:29]
	v_mfma_f32_16x16x32_bf16 v[30:33], v[190:193], v[174:177], v[30:33]
	v_mfma_f32_16x16x32_bf16 v[34:37], v[210:213], v[174:177], v[34:37]
	v_mfma_f32_16x16x32_bf16 v[38:41], v[190:193], v[182:185], v[38:41]
	v_mfma_f32_16x16x32_bf16 v[42:45], v[210:213], v[182:185], v[42:45]
	v_mfma_f32_16x16x32_bf16 v[110:113], v[206:209], v[138:141], v[110:113]
	v_mfma_f32_16x16x32_bf16 v[18:21], v[214:217], v[138:141], v[18:21]
	v_mfma_f32_16x16x32_bf16 v[22:25], v[206:209], v[170:173], v[22:25]
	v_mfma_f32_16x16x32_bf16 v[26:29], v[214:217], v[170:173], v[26:29]
	v_mfma_f32_16x16x32_bf16 v[30:33], v[206:209], v[178:181], v[30:33]
	v_mfma_f32_16x16x32_bf16 v[34:37], v[214:217], v[178:181], v[34:37]
	v_mfma_f32_16x16x32_bf16 v[38:41], v[206:209], v[186:189], v[38:41]
	v_mfma_f32_16x16x32_bf16 v[42:45], v[214:217], v[186:189], v[42:45]
	s_mov_b32 m0, s35
	v_lshl_add_u64 v[62:63], v[198:199], 0, s[64:65]
	s_barrier
	ds_read_b128 v[134:137], v65 offset:49152
	ds_read_b128 v[138:141], v65 offset:50176
	ds_read_b128 v[166:169], v65 offset:51200
	ds_read_b128 v[170:173], v65 offset:52224
	ds_read_b128 v[174:177], v65 offset:53248
	ds_read_b128 v[178:181], v65 offset:54272
	ds_read_b128 v[182:185], v65 offset:55296
	ds_read_b128 v[186:189], v65 offset:56320
	global_load_lds_dwordx4 v[62:63], off
	v_lshl_add_u64 v[62:63], v[200:201], 0, s[64:65]
	s_mov_b32 m0, s36
	s_nop 0
	global_load_lds_dwordx4 v[62:63], off
	s_barrier
; #define G8_STAGE(bufoff, gbase, voff) do { _Pragma("unroll") for (int _i = 0; _i < 2; ++_i) \
;         __builtin_amdgcn_global_load_lds((const unsigned*)((const char*)(gbase) + (voff)[_i]), (LAS unsigned*)(lds + (bufoff) + ldsw + _i * 8192), 16, 0, 0); } while (0)
; #define G8_LDA(dst, b, h) do { _Pragma("unroll") for (int m = 0; m < 4; ++m) _Pragma("unroll") for (int k = 0; k < 2; ++k) dst[m][k] = *(const LAS bf16x8*)(lds + G8_SA(b, h) + aoff + m * 2048 + k * 1024); } while (0)
; #define G8_LDB(dst, b, h) do { _Pragma("unroll") for (int n = 0; n < 2; ++n) _Pragma("unroll") for (int k = 0; k < 2; ++k) dst[n][k] = *(const LAS bf16x8*)(lds + G8_SB(b, h) + boff + n * 2048 + k * 1024); } while (0)
; #define G8_MMA(ai, bj, At, Bt) do { __builtin_amdgcn_s_setprio(1); _Pragma("unroll") for (int m = 0; m < 4; ++m) _Pragma("unroll") for (int n = 0; n < 2; ++n) _Pragma("unroll") for (int k = 0; k < 2; ++k) \
;         acc[ai][bj][m][n] = __builtin_amdgcn_mfma_f32_16x16x32_bf16(Bt[n][k], At[m][k], acc[ai][bj][m][n], 0, 0, 0); __builtin_amdgcn_s_setprio(0); } while (0)
; #define G8_WAIT_V(n) asm volatile("s_waitcnt vmcnt(" #n ")" ::: "memory")
; #define G8_WAIT_L(n) asm volatile("s_waitcnt lgkmcnt(" #n ")" ::: "memory")
; #define G8_BAR __builtin_amdgcn_s_barrier()
; #define G8_SCHED __builtin_amdgcn_sched_barrier(0)
; template <class Epi, class Sched>
; __device__ __forceinline__ void gemm_phase(int wv, LAS unsigned char* lds, const int K, const Sched& S, const Epi& E) {
;     ...
;             G8_WAIT_V(6); G8_BAR; if (full) G8_MMA(1, 1, At, B1); G8_BAR;
;             G8_LDB(B0, 1, 0); G8_SCHED; G8_LDA(At, 1, 0); G8_STAGE(G8_SA(0, 1), a2 + hstep, voffA);
;             G8_WAIT_L(8); G8_BAR; G8_WAIT_L(0); G8_MMA(0, 0, At, B0); G8_BAR; G8_SCHED;
;             G8_LDB(B1, 1, 1); G8_STAGE(G8_SB(1, 0), b3, voffB);
;             G8_BAR; G8_WAIT_L(0); G8_MMA(0, 1, At, B1); G8_BAR;
;             if (full) G8_LDA(At, 1, 1); G8_STAGE(G8_SA(1, 0), a3, voffA);
;             G8_BAR; G8_WAIT_L(0); if (full) G8_MMA(1, 0, At, B0); G8_BAR; G8_SCHED;
	s_waitcnt lgkmcnt(0)
	s_waitcnt lgkmcnt(0)
	v_mfma_f32_16x16x32_bf16 v[142:145], v[102:105], v[134:137], v[142:145]
	v_mfma_f32_16x16x32_bf16 v[146:149], v[126:129], v[134:137], v[146:149]
	v_mfma_f32_16x16x32_bf16 v[150:153], v[102:105], v[166:169], v[150:153]
	v_mfma_f32_16x16x32_bf16 v[154:157], v[126:129], v[166:169], v[154:157]
	v_mfma_f32_16x16x32_bf16 v[158:161], v[102:105], v[174:177], v[158:161]
	v_mfma_f32_16x16x32_bf16 v[162:165], v[126:129], v[174:177], v[162:165]
	v_mfma_f32_16x16x32_bf16 v[2:5], v[102:105], v[182:185], v[2:5]
	v_mfma_f32_16x16x32_bf16 v[6:9], v[126:129], v[182:185], v[6:9]
	v_mfma_f32_16x16x32_bf16 v[142:145], v[106:109], v[138:141], v[142:145]
	v_mfma_f32_16x16x32_bf16 v[146:149], v[130:133], v[138:141], v[146:149]
	v_mfma_f32_16x16x32_bf16 v[150:153], v[106:109], v[170:173], v[150:153]
	v_mfma_f32_16x16x32_bf16 v[154:157], v[130:133], v[170:173], v[154:157]
	v_mfma_f32_16x16x32_bf16 v[158:161], v[106:109], v[178:181], v[158:161]
	v_mfma_f32_16x16x32_bf16 v[162:165], v[130:133], v[178:181], v[162:165]
	v_mfma_f32_16x16x32_bf16 v[2:5], v[106:109], v[186:189], v[2:5]
	v_mfma_f32_16x16x32_bf16 v[6:9], v[130:133], v[186:189], v[6:9]
	s_barrier
	s_add_u32 s46, s20, 0x10180
	s_addc_u32 s47, s21, 0
	s_add_i32 s21, s48, s1
	v_lshl_add_u64 v[62:63], s[46:47], 0, v[58:59]
	s_mov_b32 m0, s21
	s_add_i32 s20, s21, 0x2000
	global_load_lds_dwordx4 v[62:63], off
	v_lshl_add_u64 v[62:63], s[46:47], 0, v[54:55]
	s_mov_b32 m0, s20
	s_nop 0
	global_load_lds_dwordx4 v[62:63], off
	s_waitcnt vmcnt(6)
	s_barrier
	v_mfma_f32_16x16x32_bf16 v[10:13], v[190:193], v[134:137], v[10:13]
	v_mfma_f32_16x16x32_bf16 v[14:17], v[210:213], v[134:137], v[14:17]
	v_mfma_f32_16x16x32_bf16 v[46:49], v[190:193], v[166:169], v[46:49]
	v_mfma_f32_16x16x32_bf16 v[102:105], v[210:213], v[166:169], v[114:117]
	v_mfma_f32_16x16x32_bf16 v[106:109], v[190:193], v[174:177], v[118:121]
	v_mfma_f32_16x16x32_bf16 v[114:117], v[210:213], v[174:177], v[122:125]
	v_mfma_f32_16x16x32_bf16 v[94:97], v[190:193], v[182:185], v[94:97]
	v_mfma_f32_16x16x32_bf16 v[98:101], v[210:213], v[182:185], v[98:101]
	v_mfma_f32_16x16x32_bf16 v[10:13], v[206:209], v[138:141], v[10:13]
	v_mfma_f32_16x16x32_bf16 v[14:17], v[214:217], v[138:141], v[14:17]
	v_mfma_f32_16x16x32_bf16 v[46:49], v[206:209], v[170:173], v[46:49]
	v_mfma_f32_16x16x32_bf16 v[102:105], v[214:217], v[170:173], v[102:105]
	v_mfma_f32_16x16x32_bf16 v[106:109], v[206:209], v[178:181], v[106:109]
	v_mfma_f32_16x16x32_bf16 v[114:117], v[214:217], v[178:181], v[114:117]
	v_mfma_f32_16x16x32_bf16 v[94:97], v[206:209], v[186:189], v[94:97]
	v_mfma_f32_16x16x32_bf16 v[98:101], v[214:217], v[186:189], v[98:101]
	s_barrier
	ds_read_b128 v[118:121], v0
	ds_read_b128 v[122:125], v0 offset:1024
	ds_read_b128 v[126:129], v0 offset:2048
	ds_read_b128 v[130:133], v0 offset:3072
	s_add_u32 s18, s18, 0x10180
	s_addc_u32 s19, s19, 0
	s_mov_b32 m0, s40
	v_lshl_add_u64 v[62:63], s[18:19], 0, v[60:61]
	ds_read_b128 v[134:137], v65
	ds_read_b128 v[138:141], v65 offset:1024
	ds_read_b128 v[166:169], v65 offset:2048
	ds_read_b128 v[170:173], v65 offset:3072
	ds_read_b128 v[174:177], v65 offset:4096
	ds_read_b128 v[178:181], v65 offset:5120
	ds_read_b128 v[182:185], v65 offset:6144
	ds_read_b128 v[186:189], v65 offset:7168
	global_load_lds_dwordx4 v[62:63], off
	v_lshl_add_u64 v[62:63], s[18:19], 0, v[56:57]
	s_mov_b32 m0, s4
	s_nop 0
	global_load_lds_dwordx4 v[62:63], off
	s_waitcnt lgkmcnt(8)
	s_barrier
	s_waitcnt lgkmcnt(0)
	s_waitcnt lgkmcnt(0)
	v_mfma_f32_16x16x32_bf16 v[50:53], v[118:121], v[134:137], v[50:53]
	v_mfma_f32_16x16x32_bf16 v[66:69], v[126:129], v[134:137], v[66:69]
	v_mfma_f32_16x16x32_bf16 v[70:73], v[118:121], v[166:169], v[70:73]
	v_mfma_f32_16x16x32_bf16 v[74:77], v[126:129], v[166:169], v[74:77]
	v_mfma_f32_16x16x32_bf16 v[78:81], v[118:121], v[174:177], v[78:81]
	v_mfma_f32_16x16x32_bf16 v[82:85], v[126:129], v[174:177], v[82:85]
	v_mfma_f32_16x16x32_bf16 v[86:89], v[118:121], v[182:185], v[86:89]
	v_mfma_f32_16x16x32_bf16 v[90:93], v[126:129], v[182:185], v[90:93]
	v_mfma_f32_16x16x32_bf16 v[50:53], v[122:125], v[138:141], v[50:53]
	v_mfma_f32_16x16x32_bf16 v[66:69], v[130:133], v[138:141], v[66:69]
	v_mfma_f32_16x16x32_bf16 v[70:73], v[122:125], v[170:173], v[70:73]
	v_mfma_f32_16x16x32_bf16 v[74:77], v[130:133], v[170:173], v[74:77]
	v_mfma_f32_16x16x32_bf16 v[78:81], v[122:125], v[178:181], v[78:81]
	v_mfma_f32_16x16x32_bf16 v[82:85], v[130:133], v[178:181], v[82:85]
	v_mfma_f32_16x16x32_bf16 v[86:89], v[122:125], v[186:189], v[86:89]
	v_mfma_f32_16x16x32_bf16 v[90:93], v[130:133], v[186:189], v[90:93]
	s_barrier
	s_mov_b32 m0, s39
	v_lshl_add_u64 v[62:63], s[12:13], 0, v[58:59]
	ds_read_b128 v[190:193], v204
	ds_read_b128 v[206:209], v204 offset:1024
	ds_read_b128 v[210:213], v204 offset:2048
	ds_read_b128 v[214:217], v204 offset:3072
	global_load_lds_dwordx4 v[62:63], off
	v_lshl_add_u64 v[194:195], s[12:13], 0, v[54:55]
	s_mov_b32 m0, s5
	s_nop 0
	global_load_lds_dwordx4 v[194:195], off
	s_barrier
; #define G8_STAGE(bufoff, gbase, voff) do { _Pragma("unroll") for (int _i = 0; _i < 2; ++_i) \
;         __builtin_amdgcn_global_load_lds((const unsigned*)((const char*)(gbase) + (voff)[_i]), (LAS unsigned*)(lds + (bufoff) + ldsw + _i * 8192), 16, 0, 0); } while (0)
; #define G8_LDA(dst, b, h) do { _Pragma("unroll") for (int m = 0; m < 4; ++m) _Pragma("unroll") for (int k = 0; k < 2; ++k) dst[m][k] = *(const LAS bf16x8*)(lds + G8_SA(b, h) + aoff + m * 2048 + k * 1024); } while (0)
; #define G8_LDB(dst, b, h) do { _Pragma("unroll") for (int n = 0; n < 2; ++n) _Pragma("unroll") for (int k = 0; k < 2; ++k) dst[n][k] = *(const LAS bf16x8*)(lds + G8_SB(b, h) + boff + n * 2048 + k * 1024); } while (0)
; #define G8_MMA(ai, bj, At, Bt) do { __builtin_amdgcn_s_setprio(1); _Pragma("unroll") for (int m = 0; m < 4; ++m) _Pragma("unroll") for (int n = 0; n < 2; ++n) _Pragma("unroll") for (int k = 0; k < 2; ++k) \
;         acc[ai][bj][m][n] = __builtin_amdgcn_mfma_f32_16x16x32_bf16(Bt[n][k], At[m][k], acc[ai][bj][m][n], 0, 0, 0); __builtin_amdgcn_s_setprio(0); } while (0)
; #define G8_WAIT_V(n) asm volatile("s_waitcnt vmcnt(" #n ")" ::: "memory")
; #define G8_WAIT_L(n) asm volatile("s_waitcnt lgkmcnt(" #n ")" ::: "memory")
; #define G8_BAR __builtin_amdgcn_s_barrier()
; #define G8_SCHED __builtin_amdgcn_sched_barrier(0)
; template <class Epi, class Sched>
; __device__ __forceinline__ void gemm_phase(int wv, LAS unsigned char* lds, const int K, const Sched& S, const Epi& E) {
;     ...
;             G8_WAIT_V(6); G8_BAR; if (full) G8_MMA(1, 1, At, B1); G8_BAR;
;             G8_LDB(B0, 1, 0); G8_SCHED; G8_LDA(At, 1, 0); G8_STAGE(G8_SA(0, 1), a2 + hstep, voffA);
;             G8_WAIT_L(8); G8_BAR; G8_WAIT_L(0); G8_MMA(0, 0, At, B0); G8_BAR; G8_SCHED;
;             G8_LDB(B1, 1, 1); G8_STAGE(G8_SB(1, 0), b3, voffB);
;             G8_BAR; G8_WAIT_L(0); G8_MMA(0, 1, At, B1); G8_BAR;
;             if (full) G8_LDA(At, 1, 1); G8_STAGE(G8_SA(1, 0), a3, voffA);
;             G8_BAR; G8_WAIT_L(0); if (full) G8_MMA(1, 0, At, B0); G8_BAR; G8_SCHED;
	s_waitcnt lgkmcnt(0)
	s_waitcnt lgkmcnt(0)
	v_mfma_f32_16x16x32_bf16 v[110:113], v[190:193], v[134:137], v[110:113]
	v_mfma_f32_16x16x32_bf16 v[18:21], v[210:213], v[134:137], v[18:21]
	v_mfma_f32_16x16x32_bf16 v[22:25], v[190:193], v[166:169], v[22:25]
	v_mfma_f32_16x16x32_bf16 v[26:29], v[210:213], v[166:169], v[26:29]
	v_mfma_f32_16x16x32_bf16 v[30:33], v[190:193], v[174:177], v[30:33]
	v_mfma_f32_16x16x32_bf16 v[34:37], v[210:213], v[174:177], v[34:37]
	v_mfma_f32_16x16x32_bf16 v[38:41], v[190:193], v[182:185], v[38:41]
	v_mfma_f32_16x16x32_bf16 v[42:45], v[210:213], v[182:185], v[42:45]
	v_mfma_f32_16x16x32_bf16 v[110:113], v[206:209], v[138:141], v[110:113]
	v_mfma_f32_16x16x32_bf16 v[18:21], v[214:217], v[138:141], v[18:21]
	v_mfma_f32_16x16x32_bf16 v[22:25], v[206:209], v[170:173], v[22:25]
	v_mfma_f32_16x16x32_bf16 v[26:29], v[214:217], v[170:173], v[26:29]
	v_mfma_f32_16x16x32_bf16 v[30:33], v[206:209], v[178:181], v[30:33]
	v_mfma_f32_16x16x32_bf16 v[34:37], v[214:217], v[178:181], v[34:37]
	v_mfma_f32_16x16x32_bf16 v[38:41], v[206:209], v[186:189], v[38:41]
	v_mfma_f32_16x16x32_bf16 v[42:45], v[214:217], v[186:189], v[42:45]
	s_mov_b32 m0, s25
	v_lshl_add_u64 v[204:205], s[10:11], 0, v[60:61]
	s_barrier
	ds_read_b128 v[134:137], v65 offset:16384
	ds_read_b128 v[138:141], v65 offset:17408
	ds_read_b128 v[166:169], v65 offset:18432
	ds_read_b128 v[170:173], v65 offset:19456
	ds_read_b128 v[174:177], v65 offset:20480
	ds_read_b128 v[178:181], v65 offset:21504
	ds_read_b128 v[182:185], v65 offset:22528
	ds_read_b128 v[186:189], v65 offset:23552
	global_load_lds_dwordx4 v[204:205], off
	v_lshl_add_u64 v[234:235], s[10:11], 0, v[56:57]
	s_mov_b32 m0, s26
	s_nop 0
	global_load_lds_dwordx4 v[234:235], off
	s_barrier
	s_waitcnt lgkmcnt(0)
	s_waitcnt lgkmcnt(0)
	v_mfma_f32_16x16x32_bf16 v[142:145], v[118:121], v[134:137], v[142:145]
	v_mfma_f32_16x16x32_bf16 v[146:149], v[126:129], v[134:137], v[146:149]
	v_mfma_f32_16x16x32_bf16 v[150:153], v[118:121], v[166:169], v[150:153]
	v_mfma_f32_16x16x32_bf16 v[154:157], v[126:129], v[166:169], v[154:157]
	v_mfma_f32_16x16x32_bf16 v[158:161], v[118:121], v[174:177], v[158:161]
	v_mfma_f32_16x16x32_bf16 v[162:165], v[126:129], v[174:177], v[162:165]
	v_mfma_f32_16x16x32_bf16 v[2:5], v[118:121], v[182:185], v[2:5]
	v_mfma_f32_16x16x32_bf16 v[6:9], v[126:129], v[182:185], v[6:9]
	v_mfma_f32_16x16x32_bf16 v[142:145], v[122:125], v[138:141], v[142:145]
	v_mfma_f32_16x16x32_bf16 v[146:149], v[130:133], v[138:141], v[146:149]
	v_mfma_f32_16x16x32_bf16 v[150:153], v[122:125], v[170:173], v[150:153]
	v_mfma_f32_16x16x32_bf16 v[154:157], v[130:133], v[170:173], v[154:157]
	v_mfma_f32_16x16x32_bf16 v[158:161], v[122:125], v[178:181], v[158:161]
	v_mfma_f32_16x16x32_bf16 v[162:165], v[130:133], v[178:181], v[162:165]
	v_mfma_f32_16x16x32_bf16 v[2:5], v[122:125], v[186:189], v[2:5]
	v_mfma_f32_16x16x32_bf16 v[118:121], v[130:133], v[186:189], v[6:9]
	s_barrier
	s_add_u32 s4, s12, 0x10000
	s_addc_u32 s5, s13, 0
	s_mov_b32 m0, s41
	v_lshl_add_u64 v[6:7], s[4:5], 0, v[58:59]
	global_load_lds_dwordx4 v[6:7], off
	v_lshl_add_u64 v[6:7], s[4:5], 0, v[54:55]
	s_mov_b32 m0, s38
	s_nop 0
	global_load_lds_dwordx4 v[6:7], off
	s_waitcnt vmcnt(6)
	s_barrier
	v_mfma_f32_16x16x32_bf16 v[6:9], v[190:193], v[134:137], v[10:13]
	v_mfma_f32_16x16x32_bf16 v[10:13], v[206:209], v[138:141], v[6:9]
	v_mfma_f32_16x16x32_bf16 v[6:9], v[210:213], v[134:137], v[14:17]
	v_mfma_f32_16x16x32_bf16 v[14:17], v[214:217], v[138:141], v[6:9]
	v_mfma_f32_16x16x32_bf16 v[6:9], v[190:193], v[166:169], v[46:49]
	v_mfma_f32_16x16x32_bf16 v[122:125], v[206:209], v[170:173], v[6:9]
	v_mfma_f32_16x16x32_bf16 v[6:9], v[210:213], v[166:169], v[102:105]
	v_mfma_f32_16x16x32_bf16 v[102:105], v[214:217], v[170:173], v[6:9]
	v_mfma_f32_16x16x32_bf16 v[6:9], v[190:193], v[174:177], v[106:109]
	v_mfma_f32_16x16x32_bf16 v[106:109], v[206:209], v[178:181], v[6:9]
	v_mfma_f32_16x16x32_bf16 v[6:9], v[210:213], v[174:177], v[114:117]
	v_mfma_f32_16x16x32_bf16 v[114:117], v[214:217], v[178:181], v[6:9]
	v_mfma_f32_16x16x32_bf16 v[6:9], v[190:193], v[182:185], v[94:97]
	v_mfma_f32_16x16x32_bf16 v[94:97], v[206:209], v[186:189], v[6:9]
	v_mfma_f32_16x16x32_bf16 v[6:9], v[210:213], v[182:185], v[98:101]
	v_mfma_f32_16x16x32_bf16 v[98:101], v[214:217], v[186:189], v[6:9]
	s_barrier
	s_nop 4
	ds_read_b128 v[6:9], v218
	ds_read_b128 v[126:129], v218 offset:1024
	ds_read_b128 v[130:133], v218 offset:2048
	ds_read_b128 v[134:137], v218 offset:3072
	s_add_u32 s4, s10, 0x10000
	s_addc_u32 s5, s11, 0
	s_mov_b32 m0, s27
	v_lshl_add_u64 v[46:47], s[4:5], 0, v[60:61]
	ds_read_b128 v[138:141], v65 offset:32768
	ds_read_b128 v[166:169], v65 offset:33792
	ds_read_b128 v[170:173], v65 offset:34816
	ds_read_b128 v[174:177], v65 offset:35840
	ds_read_b128 v[178:181], v65 offset:36864
	ds_read_b128 v[182:185], v65 offset:37888
	ds_read_b128 v[186:189], v65 offset:38912
	ds_read_b128 v[190:193], v65 offset:39936
	global_load_lds_dwordx4 v[46:47], off
	v_lshl_add_u64 v[46:47], s[4:5], 0, v[56:57]
	s_mov_b32 m0, s28
	s_nop 0
	global_load_lds_dwordx4 v[46:47], off
	s_waitcnt lgkmcnt(8)
	s_barrier
; #define G8_STAGE(bufoff, gbase, voff) do { _Pragma("unroll") for (int _i = 0; _i < 2; ++_i) \
;         __builtin_amdgcn_global_load_lds((const unsigned*)((const char*)(gbase) + (voff)[_i]), (LAS unsigned*)(lds + (bufoff) + ldsw + _i * 8192), 16, 0, 0); } while (0)
; #define G8_LDA(dst, b, h) do { _Pragma("unroll") for (int m = 0; m < 4; ++m) _Pragma("unroll") for (int k = 0; k < 2; ++k) dst[m][k] = *(const LAS bf16x8*)(lds + G8_SA(b, h) + aoff + m * 2048 + k * 1024); } while (0)
; #define G8_LDB(dst, b, h) do { _Pragma("unroll") for (int n = 0; n < 2; ++n) _Pragma("unroll") for (int k = 0; k < 2; ++k) dst[n][k] = *(const LAS bf16x8*)(lds + G8_SB(b, h) + boff + n * 2048 + k * 1024); } while (0)
; #define G8_MMA(ai, bj, At, Bt) do { __builtin_amdgcn_s_setprio(1); _Pragma("unroll") for (int m = 0; m < 4; ++m) _Pragma("unroll") for (int n = 0; n < 2; ++n) _Pragma("unroll") for (int k = 0; k < 2; ++k) \
;         acc[ai][bj][m][n] = __builtin_amdgcn_mfma_f32_16x16x32_bf16(Bt[n][k], At[m][k], acc[ai][bj][m][n], 0, 0, 0); __builtin_amdgcn_s_setprio(0); } while (0)
; #define G8_WAIT_V(n) asm volatile("s_waitcnt vmcnt(" #n ")" ::: "memory")
; #define G8_WAIT_L(n) asm volatile("s_waitcnt lgkmcnt(" #n ")" ::: "memory")
; #define G8_BAR __builtin_amdgcn_s_barrier()
; #define G8_SCHED __builtin_amdgcn_sched_barrier(0)
; template <class Epi, class Sched>
; __device__ __forceinline__ void gemm_phase(int wv, LAS unsigned char* lds, const int K, const Sched& S, const Epi& E) {
;     ...
;             G8_WAIT_V(6); G8_BAR; if (full) G8_MMA(1, 1, At, B1); G8_BAR;
;             G8_LDB(B0, 1, 0); G8_SCHED; G8_LDA(At, 1, 0); G8_STAGE(G8_SA(0, 1), a2 + hstep, voffA);
;             G8_WAIT_L(8); G8_BAR; G8_WAIT_L(0); G8_MMA(0, 0, At, B0); G8_BAR; G8_SCHED;
;             G8_LDB(B1, 1, 1); G8_STAGE(G8_SB(1, 0), b3, voffB);
;             G8_BAR; G8_WAIT_L(0); G8_MMA(0, 1, At, B1); G8_BAR;
;             if (full) G8_LDA(At, 1, 1); G8_STAGE(G8_SA(1, 0), a3, voffA);
;             G8_BAR; G8_WAIT_L(0); if (full) G8_MMA(1, 0, At, B0); G8_BAR; G8_SCHED;
;             G8_STAGE(G8_SB(1, 1), b3 + hstep, voffB);
;             G8_WAIT_V(6); G8_BAR; if (full) G8_MMA(1, 1, At, B1); G8_BAR;
	s_waitcnt lgkmcnt(0)
	s_waitcnt lgkmcnt(0)
	v_mfma_f32_16x16x32_bf16 v[46:49], v[6:9], v[138:141], v[50:53]
	v_mfma_f32_16x16x32_bf16 v[206:209], v[126:129], v[166:169], v[46:49]
	v_mfma_f32_16x16x32_bf16 v[46:49], v[130:133], v[138:141], v[66:69]
	v_mfma_f32_16x16x32_bf16 v[66:69], v[134:137], v[166:169], v[46:49]
	v_mfma_f32_16x16x32_bf16 v[46:49], v[6:9], v[170:173], v[70:73]
	v_mfma_f32_16x16x32_bf16 v[70:73], v[126:129], v[174:177], v[46:49]
	v_mfma_f32_16x16x32_bf16 v[46:49], v[130:133], v[170:173], v[74:77]
	v_mfma_f32_16x16x32_bf16 v[74:77], v[134:137], v[174:177], v[46:49]
	v_mfma_f32_16x16x32_bf16 v[46:49], v[6:9], v[178:181], v[78:81]
	v_mfma_f32_16x16x32_bf16 v[78:81], v[126:129], v[182:185], v[46:49]
	v_mfma_f32_16x16x32_bf16 v[46:49], v[130:133], v[178:181], v[82:85]
	v_mfma_f32_16x16x32_bf16 v[82:85], v[134:137], v[182:185], v[46:49]
	v_mfma_f32_16x16x32_bf16 v[46:49], v[6:9], v[186:189], v[86:89]
	v_mfma_f32_16x16x32_bf16 v[86:89], v[126:129], v[190:193], v[46:49]
	v_mfma_f32_16x16x32_bf16 v[46:49], v[130:133], v[186:189], v[90:93]
	v_mfma_f32_16x16x32_bf16 v[46:49], v[134:137], v[190:193], v[46:49]
	s_barrier
	s_mov_b32 m0, s43
	v_lshl_add_u64 v[50:51], v[62:63], 0, s[58:59]
	ds_read_b128 v[90:93], v219
	ds_read_b128 v[210:213], v219 offset:1024
	ds_read_b128 v[214:217], v219 offset:2048
	ds_read_b128 v[218:221], v219 offset:3072
	global_load_lds_dwordx4 v[50:51], off
	v_lshl_add_u64 v[50:51], v[194:195], 0, s[58:59]
	s_mov_b32 m0, s42
	s_nop 0
	global_load_lds_dwordx4 v[50:51], off
	s_barrier
	s_waitcnt lgkmcnt(0)
	s_waitcnt lgkmcnt(0)
	v_mfma_f32_16x16x32_bf16 v[18:21], v[214:217], v[138:141], v[18:21]
	v_mfma_f32_16x16x32_bf16 v[50:53], v[90:93], v[138:141], v[110:113]
	v_mfma_f32_16x16x32_bf16 v[138:141], v[218:221], v[166:169], v[18:21]
	v_mfma_f32_16x16x32_bf16 v[18:21], v[90:93], v[170:173], v[22:25]
	v_mfma_f32_16x16x32_bf16 v[110:113], v[210:213], v[166:169], v[50:53]
	v_mfma_f32_16x16x32_bf16 v[166:169], v[210:213], v[174:177], v[18:21]
	v_mfma_f32_16x16x32_bf16 v[18:21], v[214:217], v[170:173], v[26:29]
	v_mfma_f32_16x16x32_bf16 v[170:173], v[218:221], v[174:177], v[18:21]
	v_mfma_f32_16x16x32_bf16 v[18:21], v[90:93], v[178:181], v[30:33]
	v_mfma_f32_16x16x32_bf16 v[174:177], v[210:213], v[182:185], v[18:21]
	v_mfma_f32_16x16x32_bf16 v[18:21], v[214:217], v[178:181], v[34:37]
	v_mfma_f32_16x16x32_bf16 v[178:181], v[218:221], v[182:185], v[18:21]
	v_mfma_f32_16x16x32_bf16 v[18:21], v[90:93], v[186:189], v[38:41]
	v_mfma_f32_16x16x32_bf16 v[182:185], v[210:213], v[190:193], v[18:21]
	v_mfma_f32_16x16x32_bf16 v[18:21], v[214:217], v[186:189], v[42:45]
	v_mfma_f32_16x16x32_bf16 v[186:189], v[218:221], v[190:193], v[18:21]
	s_mov_b32 m0, s35
	s_nop 4
	v_lshl_add_u64 v[18:19], v[204:205], 0, s[58:59]
	s_barrier
	ds_read_b128 v[26:29], v65 offset:49152
	ds_read_b128 v[30:33], v65 offset:50176
	ds_read_b128 v[42:45], v65 offset:51200
	ds_read_b128 v[190:193], v65 offset:52224
	ds_read_b128 v[222:225], v65 offset:53248
	ds_read_b128 v[248:251], v65 offset:54272
	ds_read_b128 v[226:229], v65 offset:55296
	ds_read_b128 v[198:201], v65 offset:56320
	global_load_lds_dwordx4 v[18:19], off
	v_lshl_add_u64 v[18:19], v[234:235], 0, s[58:59]
	s_mov_b32 m0, s36
	s_nop 0
	global_load_lds_dwordx4 v[18:19], off
	s_barrier
	s_waitcnt lgkmcnt(0)
	s_waitcnt lgkmcnt(0)
	v_mfma_f32_16x16x32_bf16 v[18:21], v[6:9], v[26:29], v[142:145]
	v_mfma_f32_16x16x32_bf16 v[142:145], v[126:129], v[30:33], v[18:21]
	v_mfma_f32_16x16x32_bf16 v[18:21], v[130:133], v[26:29], v[146:149]
	v_mfma_f32_16x16x32_bf16 v[146:149], v[134:137], v[30:33], v[18:21]
	v_mfma_f32_16x16x32_bf16 v[18:21], v[6:9], v[42:45], v[150:153]
	v_mfma_f32_16x16x32_bf16 v[38:41], v[126:129], v[190:193], v[18:21]
	v_mfma_f32_16x16x32_bf16 v[18:21], v[130:133], v[42:45], v[154:157]
	v_mfma_f32_16x16x32_bf16 v[34:37], v[134:137], v[190:193], v[18:21]
	v_mfma_f32_16x16x32_bf16 v[18:21], v[6:9], v[222:225], v[158:161]
	v_mfma_f32_16x16x32_bf16 v[2:5], v[6:9], v[226:229], v[2:5]
	v_mfma_f32_16x16x32_bf16 v[22:25], v[126:129], v[248:251], v[18:21]
	v_mfma_f32_16x16x32_bf16 v[18:21], v[130:133], v[222:225], v[162:165]
	v_mfma_f32_16x16x32_bf16 v[6:9], v[126:129], v[198:201], v[2:5]
	v_mfma_f32_16x16x32_bf16 v[2:5], v[130:133], v[226:229], v[118:121]
	v_mfma_f32_16x16x32_bf16 v[18:21], v[134:137], v[248:251], v[18:21]
	v_mfma_f32_16x16x32_bf16 v[2:5], v[134:137], v[198:201], v[2:5]
	s_barrier
	s_add_u32 s4, s12, 0x10080
	s_addc_u32 s5, s13, 0
	s_mov_b32 m0, s21
	v_lshl_add_u64 v[50:51], s[4:5], 0, v[58:59]
	global_load_lds_dwordx4 v[50:51], off
	v_lshl_add_u64 v[50:51], s[4:5], 0, v[54:55]
	s_mov_b32 m0, s20
	s_nop 0
	global_load_lds_dwordx4 v[50:51], off
	s_waitcnt vmcnt(6)
	s_barrier
	v_mfma_f32_16x16x32_bf16 v[10:13], v[90:93], v[26:29], v[10:13]
	v_mfma_f32_16x16x32_bf16 v[118:121], v[210:213], v[30:33], v[10:13]
	v_mfma_f32_16x16x32_bf16 v[10:13], v[214:217], v[26:29], v[14:17]
	v_mfma_f32_16x16x32_bf16 v[126:129], v[218:221], v[30:33], v[10:13]
	v_mfma_f32_16x16x32_bf16 v[10:13], v[90:93], v[42:45], v[122:125]
	v_mfma_f32_16x16x32_bf16 v[50:53], v[210:213], v[190:193], v[10:13]
	v_mfma_f32_16x16x32_bf16 v[10:13], v[214:217], v[42:45], v[102:105]
	v_mfma_f32_16x16x32_bf16 v[42:45], v[218:221], v[190:193], v[10:13]
	v_mfma_f32_16x16x32_bf16 v[10:13], v[90:93], v[222:225], v[106:109]
	v_mfma_f32_16x16x32_bf16 v[30:33], v[210:213], v[248:251], v[10:13]
	v_mfma_f32_16x16x32_bf16 v[10:13], v[214:217], v[222:225], v[114:117]
	v_mfma_f32_16x16x32_bf16 v[26:29], v[218:221], v[248:251], v[10:13]
	v_mfma_f32_16x16x32_bf16 v[10:13], v[90:93], v[226:229], v[94:97]
	v_mfma_f32_16x16x32_bf16 v[14:17], v[210:213], v[198:201], v[10:13]
	v_mfma_f32_16x16x32_bf16 v[10:13], v[214:217], v[226:229], v[98:101]
	v_mfma_f32_16x16x32_bf16 v[10:13], v[218:221], v[198:201], v[10:13]
	s_barrier
; __device__ __forceinline__ unsigned pk_bf16(float lo, float hi) { unsigned r; asm volatile("v_cvt_pk_bf16_f32 %0, %1, %2" : "=v"(r) : "v"(lo), "v"(hi)); return r; }
;     __device__ __forceinline__ void operator()(const f32x4 (&acc)[2][2][4][2], const Unit& u, int wr, int wc, int fr, int fq) const {
;         const int row0 = wr * 64 + fr, col0 = wc * 32 + 8 * fq;
; #pragma unroll
;         for (int ai = 0; ai < 2; ++ai) if (ai == 0 || u.half == 0)
; #pragma unroll
;             for (int m = 0; m < 4; ++m) { const int rr = row0 + ai * HALF + m * 16; bf16_t* rowp = (bf16_t*)u.o + (size_t)rr * u.ldo + col0;
;                 const int k = u.mk + rr; const bool mir = (u.mk >= 0) && (k > 0);
;                 bf16_t* rowm = (bf16_t*)u.p1 + (size_t)(2048 - k) * u.ldo + col0;
; #pragma unroll
;                 for (int bj = 0; bj < 2; ++bj) { if (col0 + bj * HALF < u.cmax) { const f32x4 v0 = acc[ai][bj][m][0], v1 = acc[ai][bj][m][1];
;                     u32x4 w; w.x = pk_bf16(v0[0], v0[1]); w.y = pk_bf16(v0[2], v0[3]); w.z = pk_bf16(v1[0], v1[1]); w.w = pk_bf16(v1[2], v1[3]);
;                     st16_wt(rowp + bj * HALF, w);
;                     if (mir) { const float sg = u.mneg ? -1.f : 1.f; u32x4 w2; w2.x = pk_bf16(v0[0] * sg, v0[1] * sg); w2.y = pk_bf16(v0[2] * sg, v0[3] * sg); w2.z = pk_bf16(v1[0] * sg, v1[1] * sg); w2.w = pk_bf16(v1[2] * sg, v1[3] * sg);
;                         st16_wt(rowm + bj * HALF, w2); } } } }
	v_mbcnt_lo_u32_b32 v0, -1, 0
	v_mbcnt_hi_u32_b32 v0, -1, v0
	v_cvt_pk_bf16_f32 v90, v206, v207
	v_cvt_pk_bf16_f32 v91, v208, v209
	v_cvt_pk_bf16_f32 v92, v66, v67
	v_cvt_pk_bf16_f32 v93, v68, v69
	s_mov_b64 s[4:5], 0x20000
	v_and_or_b32 v94, v0, 15, s31
	v_lshrrev_b32_e32 v0, 1, v0
	v_ashrrev_i32_e32 v95, 31, v94
	v_and_or_b32 v0, v0, 24, s34
	v_lshlrev_b64 v[62:63], 10, v[94:95]
	v_lshl_add_u64 v[62:63], s[16:17], 0, v[62:63]
	v_lshlrev_b32_e32 v0, 1, v0
	v_lshl_add_u64 v[62:63], v[62:63], 0, v[0:1]
	global_store_dwordx4 v[62:63], v[90:93], off
	v_cvt_pk_bf16_f32 v66, v110, v111
	v_cvt_pk_bf16_f32 v67, v112, v113
	v_cvt_pk_bf16_f32 v68, v138, v139
	v_cvt_pk_bf16_f32 v69, v140, v141
	global_store_dwordx4 v[62:63], v[66:69], off offset:256
	s_add_i32 s37, s37, s44
	s_mov_b64 s[20:21], s[12:13]
	v_or_b32_e32 v66, 16, v94
	v_ashrrev_i32_e32 v67, 31, v66
	v_lshlrev_b64 v[66:67], 10, v[66:67]
	v_lshl_add_u64 v[66:67], s[16:17], 0, v[66:67]
	v_lshl_add_u64 v[90:91], v[66:67], 0, v[0:1]
	v_cvt_pk_bf16_f32 v66, v70, v71
	v_cvt_pk_bf16_f32 v67, v72, v73
	v_cvt_pk_bf16_f32 v68, v74, v75
	v_cvt_pk_bf16_f32 v69, v76, v77
	global_store_dwordx4 v[90:91], v[66:69], off
	s_mov_b64 s[18:19], s[10:11]
	v_mov_b32_e32 v228, 0x3e642e9d
	v_cvt_pk_bf16_f32 v66, v166, v167
	v_cvt_pk_bf16_f32 v67, v168, v169
	v_cvt_pk_bf16_f32 v68, v170, v171
	v_cvt_pk_bf16_f32 v69, v172, v173
	global_store_dwordx4 v[90:91], v[66:69], off offset:256
	s_nop 1
	v_or_b32_e32 v66, 32, v94
	v_ashrrev_i32_e32 v67, 31, v66
	v_lshlrev_b64 v[66:67], 10, v[66:67]
	v_lshl_add_u64 v[66:67], s[16:17], 0, v[66:67]
	v_lshl_add_u64 v[70:71], v[66:67], 0, v[0:1]
	v_cvt_pk_bf16_f32 v66, v78, v79
	v_cvt_pk_bf16_f32 v67, v80, v81
	v_cvt_pk_bf16_f32 v68, v82, v83
	v_cvt_pk_bf16_f32 v69, v84, v85
	global_store_dwordx4 v[70:71], v[66:69], off
	s_nop 1
	v_cvt_pk_bf16_f32 v66, v174, v175
	v_cvt_pk_bf16_f32 v67, v176, v177
	v_cvt_pk_bf16_f32 v68, v178, v179
	v_cvt_pk_bf16_f32 v69, v180, v181
	global_store_dwordx4 v[70:71], v[66:69], off offset:256
	s_nop 1
	v_or_b32_e32 v66, 48, v94
	v_ashrrev_i32_e32 v67, 31, v66
	v_lshlrev_b64 v[66:67], 10, v[66:67]
	v_lshl_add_u64 v[66:67], s[16:17], 0, v[66:67]
	v_lshl_add_u64 v[70:71], v[66:67], 0, v[0:1]
	v_cvt_pk_bf16_f32 v66, v86, v87
	v_cvt_pk_bf16_f32 v67, v88, v89
	v_cvt_pk_bf16_f32 v68, v46, v47
	v_cvt_pk_bf16_f32 v69, v48, v49
	global_store_dwordx4 v[70:71], v[66:69], off
	v_cvt_pk_bf16_f32 v46, v182, v183
	v_cvt_pk_bf16_f32 v47, v184, v185
	v_cvt_pk_bf16_f32 v48, v186, v187
	v_cvt_pk_bf16_f32 v49, v188, v189
	global_store_dwordx4 v[70:71], v[46:49], off offset:256
	s_nop 0
	v_add_co_u32_e32 v68, vcc, s56, v62
	v_cvt_pk_bf16_f32 v46, v142, v143
	v_cvt_pk_bf16_f32 v47, v144, v145
	v_lshl_add_u64 v[66:67], v[62:63], 0, s[4:5]
	s_nop 0
	v_addc_co_u32_e32 v69, vcc, 0, v63, vcc
	v_cvt_pk_bf16_f32 v48, v146, v147
	v_cvt_pk_bf16_f32 v49, v148, v149
	global_store_dwordx4 v[68:69], v[46:49], off
	s_mov_b64 s[4:5], 0x24000
	s_mov_b64 s[16:17], s[14:15]
	v_cvt_pk_bf16_f32 v46, v118, v119
	v_cvt_pk_bf16_f32 v47, v120, v121
	v_cvt_pk_bf16_f32 v48, v126, v127
	v_cvt_pk_bf16_f32 v49, v128, v129
	global_store_dwordx4 v[66:67], v[46:49], off offset:256
	v_cvt_pk_bf16_f32 v38, v38, v39
	v_cvt_pk_bf16_f32 v39, v40, v41
	v_cvt_pk_bf16_f32 v40, v34, v35
	v_cvt_pk_bf16_f32 v41, v36, v37
	s_nop 1
	v_lshl_add_u64 v[46:47], v[62:63], 0, s[4:5]
	s_mov_b32 s4, 0x24000
	v_add_co_u32_e32 v34, vcc, s4, v62
	s_mov_b64 s[4:5], 0x28000
	s_nop 0
	v_addc_co_u32_e32 v35, vcc, 0, v63, vcc
	global_store_dwordx4 v[34:35], v[38:41], off
	v_cvt_pk_bf16_f32 v34, v50, v51
	v_cvt_pk_bf16_f32 v35, v52, v53
	v_cvt_pk_bf16_f32 v36, v42, v43
	v_cvt_pk_bf16_f32 v37, v44, v45
	global_store_dwordx4 v[46:47], v[34:37], off offset:256
	v_cvt_pk_bf16_f32 v22, v22, v23
	v_cvt_pk_bf16_f32 v23, v24, v25
	v_cvt_pk_bf16_f32 v24, v18, v19
	v_cvt_pk_bf16_f32 v25, v20, v21
	s_nop 1
	v_lshl_add_u64 v[34:35], v[62:63], 0, s[4:5]
	s_mov_b32 s4, 0x28000
	v_add_co_u32_e32 v18, vcc, s4, v62
	s_mov_b64 s[4:5], 0x2c000
	s_nop 0
	v_addc_co_u32_e32 v19, vcc, 0, v63, vcc
	global_store_dwordx4 v[18:19], v[22:25], off
	v_cvt_pk_bf16_f32 v18, v30, v31
	v_cvt_pk_bf16_f32 v19, v32, v33
	v_cvt_pk_bf16_f32 v20, v26, v27
	v_cvt_pk_bf16_f32 v21, v28, v29
	global_store_dwordx4 v[34:35], v[18:21], off offset:256
	v_cvt_pk_bf16_f32 v6, v6, v7
	v_cvt_pk_bf16_f32 v7, v8, v9
	v_cvt_pk_bf16_f32 v8, v2, v3
	v_cvt_pk_bf16_f32 v9, v4, v5
	s_nop 1
	v_lshl_add_u64 v[18:19], v[62:63], 0, s[4:5]
	s_mov_b32 s4, 0x2c000
	v_add_co_u32_e32 v2, vcc, s4, v62
	s_nop 1
	v_addc_co_u32_e32 v3, vcc, 0, v63, vcc
	s_andn2_b64 vcc, exec, s[8:9]
	global_store_dwordx4 v[2:3], v[6:9], off
	v_cvt_pk_bf16_f32 v2, v14, v15
	v_cvt_pk_bf16_f32 v3, v16, v17
	v_cvt_pk_bf16_f32 v4, v10, v11
	v_cvt_pk_bf16_f32 v5, v12, v13
	global_store_dwordx4 v[18:19], v[2:5], off offset:256
	s_cbranch_vccz .LBB0_654

; #define G8_STAGE(bufoff, gbase, voff) do { _Pragma("unroll") for (int _i = 0; _i < 2; ++_i) \
;         __builtin_amdgcn_global_load_lds((const unsigned*)((const char*)(gbase) + (voff)[_i]), (LAS unsigned*)(lds + (bufoff) + ldsw + _i * 8192), 16, 0, 0); } while (0)
; #define G8_LDA(dst, b, h) do { _Pragma("unroll") for (int m = 0; m < 4; ++m) _Pragma("unroll") for (int k = 0; k < 2; ++k) dst[m][k] = *(const LAS bf16x8*)(lds + G8_SA(b, h) + aoff + m * 2048 + k * 1024); } while (0)
; #define G8_LDB(dst, b, h) do { _Pragma("unroll") for (int n = 0; n < 2; ++n) _Pragma("unroll") for (int k = 0; k < 2; ++k) dst[n][k] = *(const LAS bf16x8*)(lds + G8_SB(b, h) + boff + n * 2048 + k * 1024); } while (0)
; #define G8_MMA(ai, bj, At, Bt) do { __builtin_amdgcn_s_setprio(1); _Pragma("unroll") for (int m = 0; m < 4; ++m) _Pragma("unroll") for (int n = 0; n < 2; ++n) _Pragma("unroll") for (int k = 0; k < 2; ++k) \
;         acc[ai][bj][m][n] = __builtin_amdgcn_mfma_f32_16x16x32_bf16(Bt[n][k], At[m][k], acc[ai][bj][m][n], 0, 0, 0); __builtin_amdgcn_s_setprio(0); } while (0)
; #define G8_WAIT_L(n) asm volatile("s_waitcnt lgkmcnt(" #n ")" ::: "memory")
; #define G8_BAR __builtin_amdgcn_s_barrier()
; #define G8_SCHED __builtin_amdgcn_sched_barrier(0)
; template <class Epi, class Sched>
; __device__ __forceinline__ void gemm_phase(int wv, LAS unsigned char* lds, const int K, const Sched& S, const Epi& E) {
;     ...
;             G8_LDB(B0, 0, 0); G8_SCHED; G8_LDA(At, 0, 0); G8_STAGE(G8_SA(1, 1), a1 + hstep, voffA);
;             G8_WAIT_L(8); G8_BAR; G8_WAIT_L(0); G8_MMA(0, 0, At, B0); G8_BAR; G8_SCHED;
;             G8_LDB(B1, 0, 1); G8_STAGE(G8_SB(0, 0), b2, voffB);
;             G8_BAR; G8_WAIT_L(0); G8_MMA(0, 1, At, B1); G8_BAR;
;             if (full) G8_LDA(At, 0, 1); G8_STAGE(G8_SA(0, 0), a2, voffA);
;             G8_BAR; G8_WAIT_L(0); if (full) G8_MMA(1, 0, At, B0); G8_BAR; G8_SCHED;
.LBB0_946:
	s_add_u32 s18, s16, 0x100
	s_addc_u32 s19, s17, 0
	s_add_u32 s20, s4, s16
	s_addc_u32 s21, s5, s17
	s_add_i32 s43, 0, 0x10000
	v_add_u32_e32 v0, s43, v148
	ds_read_b128 v[150:153], v0
	ds_read_b128 v[154:157], v0 offset:1024
	ds_read_b128 v[158:161], v0 offset:2048
	ds_read_b128 v[162:165], v0 offset:3072
	s_cmp_eq_u32 s42, 4
	s_cselect_b32 s22, s8, s20
	s_cselect_b32 s20, 0, s18
	s_cselect_b32 s23, s9, s21
	s_cselect_b32 s21, 0, s19
	s_add_u32 s20, s6, s20
	s_addc_u32 s21, s7, s21
	v_lshl_add_u64 v[194:195], v[144:145], 0, s[16:17]
	s_add_i32 m0, s27, 0xc000
	ds_read_b128 v[166:169], v149
	ds_read_b128 v[170:173], v149 offset:1024
	ds_read_b128 v[174:177], v149 offset:2048
	ds_read_b128 v[178:181], v149 offset:3072
	ds_read_b128 v[182:185], v149 offset:4096
	ds_read_b128 v[186:189], v149 offset:5120
	ds_read_b128 v[190:193], v149 offset:6144
	ds_read_b128 v[198:201], v149 offset:7168
	global_load_lds_dwordx4 v[194:195], off
	v_lshl_add_u64 v[194:195], v[146:147], 0, s[16:17]
	s_add_i32 m0, s27, 0xe000
	s_nop 0
	global_load_lds_dwordx4 v[194:195], off
	s_waitcnt lgkmcnt(8)
	s_barrier
	s_waitcnt lgkmcnt(0)
	s_waitcnt lgkmcnt(0)
	v_mfma_f32_16x16x32_bf16 v[126:129], v[150:153], v[166:169], v[126:129]
	v_mfma_f32_16x16x32_bf16 v[122:125], v[158:161], v[166:169], v[122:125]
	v_mfma_f32_16x16x32_bf16 v[118:121], v[150:153], v[174:177], v[118:121]
	v_mfma_f32_16x16x32_bf16 v[110:113], v[158:161], v[174:177], v[110:113]
	v_mfma_f32_16x16x32_bf16 v[102:105], v[150:153], v[182:185], v[102:105]
	v_mfma_f32_16x16x32_bf16 v[94:97], v[158:161], v[182:185], v[94:97]
	v_mfma_f32_16x16x32_bf16 v[86:89], v[150:153], v[190:193], v[86:89]
	v_mfma_f32_16x16x32_bf16 v[78:81], v[158:161], v[190:193], v[78:81]
	v_mfma_f32_16x16x32_bf16 v[126:129], v[154:157], v[170:173], v[126:129]
	v_mfma_f32_16x16x32_bf16 v[122:125], v[162:165], v[170:173], v[122:125]
	v_mfma_f32_16x16x32_bf16 v[118:121], v[154:157], v[178:181], v[118:121]
	v_mfma_f32_16x16x32_bf16 v[110:113], v[162:165], v[178:181], v[110:113]
	v_mfma_f32_16x16x32_bf16 v[102:105], v[154:157], v[186:189], v[102:105]
	v_mfma_f32_16x16x32_bf16 v[94:97], v[162:165], v[186:189], v[94:97]
	v_mfma_f32_16x16x32_bf16 v[86:89], v[154:157], v[198:201], v[86:89]
	v_mfma_f32_16x16x32_bf16 v[78:81], v[162:165], v[198:201], v[78:81]
	s_barrier
	s_add_i32 s46, 0, 0x14000
	s_add_i32 s16, s43, s1
	v_add_u32_e32 v0, s46, v148
	v_lshl_add_u64 v[194:195], s[20:21], 0, v[136:137]
	s_mov_b32 m0, s16
	ds_read_b128 v[206:209], v0
	ds_read_b128 v[210:213], v0 offset:1024
	ds_read_b128 v[214:217], v0 offset:2048
	ds_read_b128 v[218:221], v0 offset:3072
	global_load_lds_dwordx4 v[194:195], off
	v_lshl_add_u64 v[204:205], s[20:21], 0, v[132:133]
	s_add_i32 m0, s16, 0x2000
	s_nop 0
	global_load_lds_dwordx4 v[204:205], off
	s_barrier
	s_waitcnt lgkmcnt(0)
	s_waitcnt lgkmcnt(0)
	v_mfma_f32_16x16x32_bf16 v[114:117], v[206:209], v[166:169], v[114:117]
	v_mfma_f32_16x16x32_bf16 v[106:109], v[214:217], v[166:169], v[106:109]
	v_mfma_f32_16x16x32_bf16 v[98:101], v[206:209], v[174:177], v[98:101]
	v_mfma_f32_16x16x32_bf16 v[90:93], v[214:217], v[174:177], v[90:93]
	v_mfma_f32_16x16x32_bf16 v[82:85], v[206:209], v[182:185], v[82:85]
	v_mfma_f32_16x16x32_bf16 v[74:77], v[214:217], v[182:185], v[74:77]
	v_mfma_f32_16x16x32_bf16 v[70:73], v[206:209], v[190:193], v[70:73]
	v_mfma_f32_16x16x32_bf16 v[66:69], v[214:217], v[190:193], v[66:69]
	v_mfma_f32_16x16x32_bf16 v[114:117], v[210:213], v[170:173], v[114:117]
	v_mfma_f32_16x16x32_bf16 v[106:109], v[218:221], v[170:173], v[106:109]
	v_mfma_f32_16x16x32_bf16 v[98:101], v[210:213], v[178:181], v[98:101]
	v_mfma_f32_16x16x32_bf16 v[90:93], v[218:221], v[178:181], v[90:93]
	v_mfma_f32_16x16x32_bf16 v[82:85], v[210:213], v[186:189], v[82:85]
	v_mfma_f32_16x16x32_bf16 v[74:77], v[218:221], v[186:189], v[74:77]
	v_mfma_f32_16x16x32_bf16 v[70:73], v[210:213], v[198:201], v[70:73]
	v_mfma_f32_16x16x32_bf16 v[66:69], v[218:221], v[198:201], v[66:69]
	s_mov_b32 m0, s27
	v_lshl_add_u64 v[222:223], s[22:23], 0, v[138:139]
	s_barrier
	ds_read_b128 v[166:169], v149 offset:16384
	ds_read_b128 v[170:173], v149 offset:17408
	ds_read_b128 v[174:177], v149 offset:18432
	ds_read_b128 v[178:181], v149 offset:19456
	ds_read_b128 v[182:185], v149 offset:20480
	ds_read_b128 v[186:189], v149 offset:21504
	ds_read_b128 v[190:193], v149 offset:22528
	ds_read_b128 v[198:201], v149 offset:23552
	global_load_lds_dwordx4 v[222:223], off
	v_lshl_add_u64 v[224:225], s[22:23], 0, v[134:135]
	s_mov_b32 m0, s30
	s_nop 0
	global_load_lds_dwordx4 v[224:225], off
	s_barrier
	s_waitcnt lgkmcnt(0)
	s_waitcnt lgkmcnt(0)
	v_mfma_f32_16x16x32_bf16 v[62:65], v[150:153], v[166:169], v[62:65]
	v_mfma_f32_16x16x32_bf16 v[58:61], v[158:161], v[166:169], v[58:61]
	v_mfma_f32_16x16x32_bf16 v[54:57], v[150:153], v[174:177], v[54:57]
	v_mfma_f32_16x16x32_bf16 v[46:49], v[158:161], v[174:177], v[46:49]
	v_mfma_f32_16x16x32_bf16 v[38:41], v[150:153], v[182:185], v[38:41]
	v_mfma_f32_16x16x32_bf16 v[30:33], v[158:161], v[182:185], v[30:33]
	v_mfma_f32_16x16x32_bf16 v[22:25], v[150:153], v[190:193], v[22:25]
	v_mfma_f32_16x16x32_bf16 v[14:17], v[158:161], v[190:193], v[14:17]
	v_mfma_f32_16x16x32_bf16 v[62:65], v[154:157], v[170:173], v[62:65]
	v_mfma_f32_16x16x32_bf16 v[58:61], v[162:165], v[170:173], v[58:61]
	v_mfma_f32_16x16x32_bf16 v[54:57], v[154:157], v[178:181], v[54:57]
	v_mfma_f32_16x16x32_bf16 v[46:49], v[162:165], v[178:181], v[46:49]
	v_mfma_f32_16x16x32_bf16 v[38:41], v[154:157], v[186:189], v[38:41]
	v_mfma_f32_16x16x32_bf16 v[30:33], v[162:165], v[186:189], v[30:33]
	v_mfma_f32_16x16x32_bf16 v[22:25], v[154:157], v[198:201], v[22:25]
	v_mfma_f32_16x16x32_bf16 v[14:17], v[162:165], v[198:201], v[14:17]
	s_barrier
; #define G8_STAGE(bufoff, gbase, voff) do { _Pragma("unroll") for (int _i = 0; _i < 2; ++_i) \
;         __builtin_amdgcn_global_load_lds((const unsigned*)((const char*)(gbase) + (voff)[_i]), (LAS unsigned*)(lds + (bufoff) + ldsw + _i * 8192), 16, 0, 0); } while (0)
; #define G8_LDA(dst, b, h) do { _Pragma("unroll") for (int m = 0; m < 4; ++m) _Pragma("unroll") for (int k = 0; k < 2; ++k) dst[m][k] = *(const LAS bf16x8*)(lds + G8_SA(b, h) + aoff + m * 2048 + k * 1024); } while (0)
; #define G8_LDB(dst, b, h) do { _Pragma("unroll") for (int n = 0; n < 2; ++n) _Pragma("unroll") for (int k = 0; k < 2; ++k) dst[n][k] = *(const LAS bf16x8*)(lds + G8_SB(b, h) + boff + n * 2048 + k * 1024); } while (0)
; #define G8_MMA(ai, bj, At, Bt) do { __builtin_amdgcn_s_setprio(1); _Pragma("unroll") for (int m = 0; m < 4; ++m) _Pragma("unroll") for (int n = 0; n < 2; ++n) _Pragma("unroll") for (int k = 0; k < 2; ++k) \
;         acc[ai][bj][m][n] = __builtin_amdgcn_mfma_f32_16x16x32_bf16(Bt[n][k], At[m][k], acc[ai][bj][m][n], 0, 0, 0); __builtin_amdgcn_s_setprio(0); } while (0)
; #define G8_WAIT_V(n) asm volatile("s_waitcnt vmcnt(" #n ")" ::: "memory")
; #define G8_WAIT_L(n) asm volatile("s_waitcnt lgkmcnt(" #n ")" ::: "memory")
; #define G8_BAR __builtin_amdgcn_s_barrier()
; #define G8_SCHED __builtin_amdgcn_sched_barrier(0)
; template <class Epi, class Sched>
; __device__ __forceinline__ void gemm_phase(int wv, LAS unsigned char* lds, const int K, const Sched& S, const Epi& E) {
;     ...
;             G8_STAGE(G8_SB(0, 1), b2 + hstep, voffB);
;             G8_WAIT_V(6); G8_BAR; if (full) G8_MMA(1, 1, At, B1); G8_BAR;
;             G8_LDB(B0, 1, 0); G8_SCHED; G8_LDA(At, 1, 0); G8_STAGE(G8_SA(0, 1), a2 + hstep, voffA);
;             G8_WAIT_L(8); G8_BAR; G8_WAIT_L(0); G8_MMA(0, 0, At, B0); G8_BAR; G8_SCHED;
;             G8_LDB(B1, 1, 1); G8_STAGE(G8_SB(1, 0), b3, voffB);
;             G8_BAR; G8_WAIT_L(0); G8_MMA(0, 1, At, B1); G8_BAR;
;             if (full) G8_LDA(At, 1, 1); G8_STAGE(G8_SA(1, 0), a3, voffA);
;             G8_BAR; G8_WAIT_L(0); if (full) G8_MMA(1, 0, At, B0); G8_BAR; G8_SCHED;
	s_add_u32 s16, s20, 0x20000
	s_addc_u32 s17, s21, 0
	s_add_i32 s43, s46, s1
	v_lshl_add_u64 v[150:151], s[16:17], 0, v[136:137]
	s_mov_b32 m0, s43
	s_nop 0
	global_load_lds_dwordx4 v[150:151], off
	v_lshl_add_u64 v[150:151], s[16:17], 0, v[132:133]
	s_add_i32 m0, s43, 0x2000
	s_nop 0
	global_load_lds_dwordx4 v[150:151], off
	s_waitcnt vmcnt(6)
	s_barrier
	v_mfma_f32_16x16x32_bf16 v[50:53], v[206:209], v[166:169], v[50:53]
	v_mfma_f32_16x16x32_bf16 v[42:45], v[214:217], v[166:169], v[42:45]
	v_mfma_f32_16x16x32_bf16 v[34:37], v[206:209], v[174:177], v[34:37]
	v_mfma_f32_16x16x32_bf16 v[26:29], v[214:217], v[174:177], v[26:29]
	v_mfma_f32_16x16x32_bf16 v[18:21], v[206:209], v[182:185], v[18:21]
	v_mfma_f32_16x16x32_bf16 v[10:13], v[214:217], v[182:185], v[10:13]
	v_mfma_f32_16x16x32_bf16 v[6:9], v[206:209], v[190:193], v[6:9]
	v_mfma_f32_16x16x32_bf16 v[2:5], v[214:217], v[190:193], v[2:5]
	v_mfma_f32_16x16x32_bf16 v[50:53], v[210:213], v[170:173], v[50:53]
	v_mfma_f32_16x16x32_bf16 v[42:45], v[218:221], v[170:173], v[42:45]
	v_mfma_f32_16x16x32_bf16 v[34:37], v[210:213], v[178:181], v[34:37]
	v_mfma_f32_16x16x32_bf16 v[26:29], v[218:221], v[178:181], v[26:29]
	v_mfma_f32_16x16x32_bf16 v[18:21], v[210:213], v[186:189], v[18:21]
	v_mfma_f32_16x16x32_bf16 v[10:13], v[218:221], v[186:189], v[10:13]
	v_mfma_f32_16x16x32_bf16 v[6:9], v[210:213], v[198:201], v[6:9]
	v_mfma_f32_16x16x32_bf16 v[2:5], v[218:221], v[198:201], v[2:5]
	s_add_i32 s43, 0, 0x18000
	v_add_u32_e32 v0, s43, v148
	s_barrier
	ds_read_b128 v[150:153], v0
	ds_read_b128 v[154:157], v0 offset:1024
	ds_read_b128 v[158:161], v0 offset:2048
	ds_read_b128 v[162:165], v0 offset:3072
	s_add_u32 s16, s22, 0x20000
	s_addc_u32 s17, s23, 0
	s_mov_b32 m0, s31
	v_lshl_add_u64 v[206:207], s[16:17], 0, v[138:139]
	ds_read_b128 v[166:169], v149 offset:32768
	ds_read_b128 v[170:173], v149 offset:33792
	ds_read_b128 v[174:177], v149 offset:34816
	ds_read_b128 v[178:181], v149 offset:35840
	ds_read_b128 v[182:185], v149 offset:36864
	ds_read_b128 v[186:189], v149 offset:37888
	ds_read_b128 v[190:193], v149 offset:38912
	ds_read_b128 v[198:201], v149 offset:39936
	global_load_lds_dwordx4 v[206:207], off
	v_lshl_add_u64 v[206:207], s[16:17], 0, v[134:135]
	s_mov_b32 m0, s34
	s_nop 0
	global_load_lds_dwordx4 v[206:207], off
	s_waitcnt lgkmcnt(8)
	s_barrier
	s_waitcnt lgkmcnt(0)
	s_waitcnt lgkmcnt(0)
	v_mfma_f32_16x16x32_bf16 v[126:129], v[150:153], v[166:169], v[126:129]
	v_mfma_f32_16x16x32_bf16 v[122:125], v[158:161], v[166:169], v[122:125]
	v_mfma_f32_16x16x32_bf16 v[118:121], v[150:153], v[174:177], v[118:121]
	v_mfma_f32_16x16x32_bf16 v[110:113], v[158:161], v[174:177], v[110:113]
	v_mfma_f32_16x16x32_bf16 v[102:105], v[150:153], v[182:185], v[102:105]
	v_mfma_f32_16x16x32_bf16 v[94:97], v[158:161], v[182:185], v[94:97]
	v_mfma_f32_16x16x32_bf16 v[86:89], v[150:153], v[190:193], v[86:89]
	v_mfma_f32_16x16x32_bf16 v[78:81], v[158:161], v[190:193], v[78:81]
	v_mfma_f32_16x16x32_bf16 v[126:129], v[154:157], v[170:173], v[126:129]
	v_mfma_f32_16x16x32_bf16 v[122:125], v[162:165], v[170:173], v[122:125]
	v_mfma_f32_16x16x32_bf16 v[118:121], v[154:157], v[178:181], v[118:121]
	v_mfma_f32_16x16x32_bf16 v[110:113], v[162:165], v[178:181], v[110:113]
	v_mfma_f32_16x16x32_bf16 v[102:105], v[154:157], v[186:189], v[102:105]
	v_mfma_f32_16x16x32_bf16 v[94:97], v[162:165], v[186:189], v[94:97]
	v_mfma_f32_16x16x32_bf16 v[86:89], v[154:157], v[198:201], v[86:89]
	v_mfma_f32_16x16x32_bf16 v[78:81], v[162:165], v[198:201], v[78:81]
	s_barrier
	s_add_i32 s22, 0, 0x1c000
	s_add_i32 s16, s43, s1
	v_add_u32_e32 v0, s22, v148
	v_lshl_add_u64 v[194:195], v[194:195], 0, s[58:59]
	s_mov_b32 m0, s16
	ds_read_b128 v[206:209], v0
	ds_read_b128 v[210:213], v0 offset:1024
	ds_read_b128 v[214:217], v0 offset:2048
	ds_read_b128 v[218:221], v0 offset:3072
	global_load_lds_dwordx4 v[194:195], off
	v_lshl_add_u64 v[194:195], v[204:205], 0, s[58:59]
	s_add_i32 m0, s16, 0x2000
	s_nop 0
	global_load_lds_dwordx4 v[194:195], off
	s_barrier
	s_waitcnt lgkmcnt(0)
	s_waitcnt lgkmcnt(0)
	v_mfma_f32_16x16x32_bf16 v[114:117], v[206:209], v[166:169], v[114:117]
	v_mfma_f32_16x16x32_bf16 v[106:109], v[214:217], v[166:169], v[106:109]
	v_mfma_f32_16x16x32_bf16 v[98:101], v[206:209], v[174:177], v[98:101]
	v_mfma_f32_16x16x32_bf16 v[90:93], v[214:217], v[174:177], v[90:93]
	v_mfma_f32_16x16x32_bf16 v[82:85], v[206:209], v[182:185], v[82:85]
	v_mfma_f32_16x16x32_bf16 v[74:77], v[214:217], v[182:185], v[74:77]
	v_mfma_f32_16x16x32_bf16 v[70:73], v[206:209], v[190:193], v[70:73]
	v_mfma_f32_16x16x32_bf16 v[66:69], v[214:217], v[190:193], v[66:69]
	v_mfma_f32_16x16x32_bf16 v[114:117], v[210:213], v[170:173], v[114:117]
	v_mfma_f32_16x16x32_bf16 v[106:109], v[218:221], v[170:173], v[106:109]
	v_mfma_f32_16x16x32_bf16 v[98:101], v[210:213], v[178:181], v[98:101]
	v_mfma_f32_16x16x32_bf16 v[90:93], v[218:221], v[178:181], v[90:93]
	v_mfma_f32_16x16x32_bf16 v[82:85], v[210:213], v[186:189], v[82:85]
	v_mfma_f32_16x16x32_bf16 v[74:77], v[218:221], v[186:189], v[74:77]
	v_mfma_f32_16x16x32_bf16 v[70:73], v[210:213], v[198:201], v[70:73]
	v_mfma_f32_16x16x32_bf16 v[66:69], v[218:221], v[198:201], v[66:69]
	s_mov_b32 m0, s39
	v_lshl_add_u64 v[194:195], v[222:223], 0, s[58:59]
	s_barrier
	ds_read_b128 v[166:169], v149 offset:49152
	ds_read_b128 v[170:173], v149 offset:50176
	ds_read_b128 v[174:177], v149 offset:51200
	ds_read_b128 v[178:181], v149 offset:52224
	ds_read_b128 v[182:185], v149 offset:53248
	ds_read_b128 v[186:189], v149 offset:54272
	ds_read_b128 v[190:193], v149 offset:55296
	ds_read_b128 v[198:201], v149 offset:56320
	global_load_lds_dwordx4 v[194:195], off
	v_lshl_add_u64 v[194:195], v[224:225], 0, s[58:59]
	s_mov_b32 m0, s40
	s_nop 0
	global_load_lds_dwordx4 v[194:195], off
	s_barrier
; #define G8_STAGE(bufoff, gbase, voff) do { _Pragma("unroll") for (int _i = 0; _i < 2; ++_i) \
;         __builtin_amdgcn_global_load_lds((const unsigned*)((const char*)(gbase) + (voff)[_i]), (LAS unsigned*)(lds + (bufoff) + ldsw + _i * 8192), 16, 0, 0); } while (0)
; #define G8_MMA(ai, bj, At, Bt) do { __builtin_amdgcn_s_setprio(1); _Pragma("unroll") for (int m = 0; m < 4; ++m) _Pragma("unroll") for (int n = 0; n < 2; ++n) _Pragma("unroll") for (int k = 0; k < 2; ++k) \
;         acc[ai][bj][m][n] = __builtin_amdgcn_mfma_f32_16x16x32_bf16(Bt[n][k], At[m][k], acc[ai][bj][m][n], 0, 0, 0); __builtin_amdgcn_s_setprio(0); } while (0)
; #define G8_WAIT_V(n) asm volatile("s_waitcnt vmcnt(" #n ")" ::: "memory")
; #define G8_WAIT_L(n) asm volatile("s_waitcnt lgkmcnt(" #n ")" ::: "memory")
; #define G8_BAR __builtin_amdgcn_s_barrier()
; #define G8_SCHED __builtin_amdgcn_sched_barrier(0)
; template <class Epi, class Sched>
; __device__ __forceinline__ void gemm_phase(int wv, LAS unsigned char* lds, const int K, const Sched& S, const Epi& E) {
;     ...
;         for (int t = 0; t < nt; t += 2) {
;     ...
;             G8_BAR; G8_WAIT_L(0); if (full) G8_MMA(1, 0, At, B0); G8_BAR; G8_SCHED;
;             G8_STAGE(G8_SB(1, 1), b3 + hstep, voffB);
;             G8_WAIT_V(6); G8_BAR; if (full) G8_MMA(1, 1, At, B1); G8_BAR;
	s_waitcnt lgkmcnt(0)
	s_waitcnt lgkmcnt(0)
	v_mfma_f32_16x16x32_bf16 v[62:65], v[150:153], v[166:169], v[62:65]
	v_mfma_f32_16x16x32_bf16 v[58:61], v[158:161], v[166:169], v[58:61]
	v_mfma_f32_16x16x32_bf16 v[54:57], v[150:153], v[174:177], v[54:57]
	v_mfma_f32_16x16x32_bf16 v[46:49], v[158:161], v[174:177], v[46:49]
	v_mfma_f32_16x16x32_bf16 v[38:41], v[150:153], v[182:185], v[38:41]
	v_mfma_f32_16x16x32_bf16 v[30:33], v[158:161], v[182:185], v[30:33]
	v_mfma_f32_16x16x32_bf16 v[22:25], v[150:153], v[190:193], v[22:25]
	v_mfma_f32_16x16x32_bf16 v[14:17], v[158:161], v[190:193], v[14:17]
	v_mfma_f32_16x16x32_bf16 v[62:65], v[154:157], v[170:173], v[62:65]
	v_mfma_f32_16x16x32_bf16 v[58:61], v[162:165], v[170:173], v[58:61]
	v_mfma_f32_16x16x32_bf16 v[54:57], v[154:157], v[178:181], v[54:57]
	v_mfma_f32_16x16x32_bf16 v[46:49], v[162:165], v[178:181], v[46:49]
	v_mfma_f32_16x16x32_bf16 v[38:41], v[154:157], v[186:189], v[38:41]
	v_mfma_f32_16x16x32_bf16 v[30:33], v[162:165], v[186:189], v[30:33]
	v_mfma_f32_16x16x32_bf16 v[22:25], v[154:157], v[198:201], v[22:25]
	v_mfma_f32_16x16x32_bf16 v[14:17], v[162:165], v[198:201], v[14:17]
	s_barrier
	s_add_u32 s16, s20, 0x20080
	s_addc_u32 s17, s21, 0
	s_add_i32 s20, s22, s1
	v_lshl_add_u64 v[150:151], s[16:17], 0, v[136:137]
	s_mov_b32 m0, s20
	s_nop 0
	global_load_lds_dwordx4 v[150:151], off
	v_lshl_add_u64 v[150:151], s[16:17], 0, v[132:133]
	s_add_i32 m0, s20, 0x2000
	s_nop 0
	global_load_lds_dwordx4 v[150:151], off
	s_waitcnt vmcnt(6)
	s_barrier
	v_mfma_f32_16x16x32_bf16 v[50:53], v[206:209], v[166:169], v[50:53]
	v_mfma_f32_16x16x32_bf16 v[42:45], v[214:217], v[166:169], v[42:45]
	v_mfma_f32_16x16x32_bf16 v[34:37], v[206:209], v[174:177], v[34:37]
	v_mfma_f32_16x16x32_bf16 v[26:29], v[214:217], v[174:177], v[26:29]
	v_mfma_f32_16x16x32_bf16 v[18:21], v[206:209], v[182:185], v[18:21]
	v_mfma_f32_16x16x32_bf16 v[10:13], v[214:217], v[182:185], v[10:13]
	v_mfma_f32_16x16x32_bf16 v[6:9], v[206:209], v[190:193], v[6:9]
	v_mfma_f32_16x16x32_bf16 v[2:5], v[214:217], v[190:193], v[2:5]
	v_mfma_f32_16x16x32_bf16 v[50:53], v[210:213], v[170:173], v[50:53]
	v_mfma_f32_16x16x32_bf16 v[42:45], v[218:221], v[170:173], v[42:45]
	v_mfma_f32_16x16x32_bf16 v[34:37], v[210:213], v[178:181], v[34:37]
	v_mfma_f32_16x16x32_bf16 v[26:29], v[218:221], v[178:181], v[26:29]
	v_mfma_f32_16x16x32_bf16 v[18:21], v[210:213], v[186:189], v[18:21]
	v_mfma_f32_16x16x32_bf16 v[10:13], v[218:221], v[186:189], v[10:13]
	v_mfma_f32_16x16x32_bf16 v[6:9], v[210:213], v[198:201], v[6:9]
	v_mfma_f32_16x16x32_bf16 v[2:5], v[218:221], v[198:201], v[2:5]
	s_add_i32 s42, s42, 2
	s_cmp_gt_u32 s42, 5
	s_mov_b64 s[16:17], s[18:19]
	s_barrier
	s_cbranch_scc0 .LBB0_946
; __device__ __forceinline__ unsigned pk_bf16(float lo, float hi) { unsigned r; asm volatile("v_cvt_pk_bf16_f32 %0, %1, %2" : "=v"(r) : "v"(lo), "v"(hi)); return r; }
; __device__ __forceinline__ int otid(int wv) { int ln; asm volatile("v_mbcnt_lo_u32_b32 %0, -1, 0\n\tv_mbcnt_hi_u32_b32 %0, -1, %0" : "=v"(ln)); return wv * 64 + ln; }
; #define G8_WAIT_V(n) asm volatile("s_waitcnt vmcnt(" #n ")" ::: "memory")
; #define G8_BAR __builtin_amdgcn_s_barrier()
; template <class Epi, class Sched>
; __device__ __forceinline__ void gemm_phase(int wv, LAS unsigned char* lds, const int K, const Sched& S, const Epi& E) {
;     ...
;         { const int t2 = otid(wv); E(acc, cur, wr, wc, t2 & 15, (t2 >> 4) & 3); }
;         if (!has_next) break;
;     ...
;     G8_WAIT_V(0);
;     if (wr == 0) G8_BAR;
;     G8_BAR;
;     __device__ __forceinline__ void operator()(const f32x4 (&acc)[2][2][4][2], const Unit& u, int wr, int wc, int fr, int fq) const {
;         const int row0 = wr * 64 + fr, col0 = wc * 32 + 8 * fq;
; #pragma unroll
;         for (int ai = 0; ai < 2; ++ai) if (ai == 0 || u.half == 0)
; #pragma unroll
;             for (int m = 0; m < 4; ++m) { const int rr = row0 + ai * HALF + m * 16; bf16_t* rowp = (bf16_t*)u.o + (size_t)rr * u.ldo + col0;
;                 const int k = u.mk + rr; const bool mir = (u.mk >= 0) && (k > 0);
;                 bf16_t* rowm = (bf16_t*)u.p1 + (size_t)(2048 - k) * u.ldo + col0;
; #pragma unroll
;                 for (int bj = 0; bj < 2; ++bj) { if (col0 + bj * HALF < u.cmax) { const f32x4 v0 = acc[ai][bj][m][0], v1 = acc[ai][bj][m][1];
;                     u32x4 w; w.x = pk_bf16(v0[0], v0[1]); w.y = pk_bf16(v0[2], v0[3]); w.z = pk_bf16(v1[0], v1[1]); w.w = pk_bf16(v1[2], v1[3]);
;                     st16_wt(rowp + bj * HALF, w);
;                     if (mir) { const float sg = u.mneg ? -1.f : 1.f; u32x4 w2; w2.x = pk_bf16(v0[0] * sg, v0[1] * sg); w2.y = pk_bf16(v0[2] * sg, v0[3] * sg); w2.z = pk_bf16(v1[0] * sg, v1[1] * sg); w2.w = pk_bf16(v1[2] * sg, v1[3] * sg);
;                         st16_wt(rowm + bj * HALF, w2); } } } }
	v_mbcnt_lo_u32_b32 v0, -1, 0
	v_mbcnt_hi_u32_b32 v0, -1, v0
	v_cvt_pk_bf16_f32 v126, v126, v127
	v_cvt_pk_bf16_f32 v127, v128, v129
	v_cvt_pk_bf16_f32 v128, v122, v123
	v_cvt_pk_bf16_f32 v129, v124, v125
	s_mov_b64 s[4:5], 0x40000
	v_and_or_b32 v146, v0, 15, s37
	v_lshrrev_b32_e32 v0, 1, v0
	v_ashrrev_i32_e32 v147, 31, v146
	v_and_or_b32 v0, v0, 24, s38
	v_lshlrev_b64 v[144:145], 11, v[146:147]
	v_lshl_add_u64 v[144:145], s[14:15], 0, v[144:145]
	v_lshlrev_b32_e32 v0, 1, v0
	v_lshl_add_u64 v[144:145], v[144:145], 0, v[0:1]
	global_store_dwordx4 v[144:145], v[126:129], off
	v_cvt_pk_bf16_f32 v114, v114, v115
	v_cvt_pk_bf16_f32 v115, v116, v117
	v_cvt_pk_bf16_f32 v116, v106, v107
	v_or_b32_e32 v106, 16, v146
	v_ashrrev_i32_e32 v107, 31, v106
	v_lshlrev_b64 v[106:107], 11, v[106:107]
	v_lshl_add_u64 v[106:107], s[14:15], 0, v[106:107]
	v_cvt_pk_bf16_f32 v117, v108, v109
	global_store_dwordx4 v[144:145], v[114:117], off offset:256
	s_mov_b64 s[16:17], s[8:9]
	s_nop 0
	v_lshl_add_u64 v[114:115], v[106:107], 0, v[0:1]
	v_cvt_pk_bf16_f32 v106, v118, v119
	v_cvt_pk_bf16_f32 v107, v120, v121
	v_cvt_pk_bf16_f32 v108, v110, v111
	v_cvt_pk_bf16_f32 v109, v112, v113
	global_store_dwordx4 v[114:115], v[106:109], off
	v_cvt_pk_bf16_f32 v98, v98, v99
	v_cvt_pk_bf16_f32 v99, v100, v101
	v_cvt_pk_bf16_f32 v100, v90, v91
	v_or_b32_e32 v90, 32, v146
	v_ashrrev_i32_e32 v91, 31, v90
	v_lshlrev_b64 v[90:91], 11, v[90:91]
	v_lshl_add_u64 v[90:91], s[14:15], 0, v[90:91]
	v_cvt_pk_bf16_f32 v101, v92, v93
	global_store_dwordx4 v[114:115], v[98:101], off offset:256
	s_nop 1
	v_lshl_add_u64 v[98:99], v[90:91], 0, v[0:1]
	v_cvt_pk_bf16_f32 v90, v102, v103
	v_cvt_pk_bf16_f32 v91, v104, v105
	v_cvt_pk_bf16_f32 v92, v94, v95
	v_cvt_pk_bf16_f32 v93, v96, v97
	global_store_dwordx4 v[98:99], v[90:93], off
	v_cvt_pk_bf16_f32 v82, v82, v83
	v_cvt_pk_bf16_f32 v83, v84, v85
	v_cvt_pk_bf16_f32 v84, v74, v75
	v_or_b32_e32 v74, 48, v146
	v_ashrrev_i32_e32 v75, 31, v74
	v_lshlrev_b64 v[74:75], 11, v[74:75]
	v_lshl_add_u64 v[74:75], s[14:15], 0, v[74:75]
	v_cvt_pk_bf16_f32 v85, v76, v77
	global_store_dwordx4 v[98:99], v[82:85], off offset:256
	s_mov_b64 s[14:15], s[12:13]
	s_nop 0
	v_lshl_add_u64 v[82:83], v[74:75], 0, v[0:1]
	v_cvt_pk_bf16_f32 v74, v86, v87
	v_cvt_pk_bf16_f32 v75, v88, v89
	v_cvt_pk_bf16_f32 v76, v78, v79
	v_cvt_pk_bf16_f32 v77, v80, v81
	global_store_dwordx4 v[82:83], v[74:77], off
	v_cvt_pk_bf16_f32 v70, v70, v71
	v_cvt_pk_bf16_f32 v71, v72, v73
	v_cvt_pk_bf16_f32 v72, v66, v67
	v_lshl_add_u64 v[66:67], v[144:145], 0, s[4:5]
	s_mov_b32 s4, 0x40000
	v_cvt_pk_bf16_f32 v73, v68, v69
	global_store_dwordx4 v[82:83], v[70:73], off offset:256
	v_cvt_pk_bf16_f32 v62, v62, v63
	v_cvt_pk_bf16_f32 v63, v64, v65
	v_cvt_pk_bf16_f32 v64, v58, v59
	v_add_co_u32_e32 v58, vcc, s4, v144
	v_cvt_pk_bf16_f32 v65, v60, v61
	s_mov_b64 s[4:5], 0x48000
	s_nop 0
	v_addc_co_u32_e32 v59, vcc, 0, v145, vcc
	global_store_dwordx4 v[58:59], v[62:65], off
	v_cvt_pk_bf16_f32 v50, v50, v51
	v_cvt_pk_bf16_f32 v51, v52, v53
	v_cvt_pk_bf16_f32 v52, v42, v43
	v_cvt_pk_bf16_f32 v53, v44, v45
	global_store_dwordx4 v[66:67], v[50:53], off offset:256
	v_cvt_pk_bf16_f32 v42, v54, v55
	v_cvt_pk_bf16_f32 v43, v56, v57
	v_cvt_pk_bf16_f32 v44, v46, v47
	v_cvt_pk_bf16_f32 v45, v48, v49
	s_nop 1
	v_lshl_add_u64 v[50:51], v[144:145], 0, s[4:5]
	s_mov_b32 s4, 0x48000
	v_add_co_u32_e32 v46, vcc, s4, v144
	s_mov_b64 s[4:5], 0x50000
	s_nop 0
	v_addc_co_u32_e32 v47, vcc, 0, v145, vcc
	global_store_dwordx4 v[46:47], v[42:45], off
	v_cvt_pk_bf16_f32 v34, v34, v35
	v_cvt_pk_bf16_f32 v35, v36, v37
	v_cvt_pk_bf16_f32 v36, v26, v27
	v_cvt_pk_bf16_f32 v37, v28, v29
	global_store_dwordx4 v[50:51], v[34:37], off offset:256
	v_cvt_pk_bf16_f32 v26, v38, v39
	v_cvt_pk_bf16_f32 v27, v40, v41
	v_cvt_pk_bf16_f32 v28, v30, v31
	v_cvt_pk_bf16_f32 v29, v32, v33
	s_nop 1
	v_lshl_add_u64 v[34:35], v[144:145], 0, s[4:5]
	s_mov_b32 s4, 0x50000
	v_add_co_u32_e32 v30, vcc, s4, v144
	s_mov_b64 s[4:5], 0x58000
	s_nop 0
	v_addc_co_u32_e32 v31, vcc, 0, v145, vcc
	global_store_dwordx4 v[30:31], v[26:29], off
	v_cvt_pk_bf16_f32 v18, v18, v19
	v_cvt_pk_bf16_f32 v19, v20, v21
	v_cvt_pk_bf16_f32 v20, v10, v11
	v_cvt_pk_bf16_f32 v21, v12, v13
	global_store_dwordx4 v[34:35], v[18:21], off offset:256
	v_cvt_pk_bf16_f32 v10, v22, v23
	v_cvt_pk_bf16_f32 v11, v24, v25
	v_cvt_pk_bf16_f32 v12, v14, v15
	v_cvt_pk_bf16_f32 v13, v16, v17
	s_nop 1
	v_lshl_add_u64 v[18:19], v[144:145], 0, s[4:5]
	s_mov_b32 s4, 0x58000
	v_add_co_u32_e32 v14, vcc, s4, v144
	s_nop 1
	v_addc_co_u32_e32 v15, vcc, 0, v145, vcc
	s_and_b64 vcc, exec, s[10:11]
	global_store_dwordx4 v[14:15], v[10:13], off
	v_cvt_pk_bf16_f32 v6, v6, v7
	v_cvt_pk_bf16_f32 v7, v8, v9
	v_cvt_pk_bf16_f32 v8, v2, v3
	v_cvt_pk_bf16_f32 v9, v4, v5
	global_store_dwordx4 v[18:19], v[6:9], off offset:256
	s_cbranch_vccz .LBB0_943
	s_waitcnt vmcnt(0)
	s_cmpk_gt_u32 s0, 0xff
	s_cbranch_scc1 .LBB0_950
	s_barrier
